# in-proj and FFN-up K loops: LDS-DMA pieces take scalar-base addresses (voff32 + SGPR pair) instead of a 64-bit VALU add per piece; 16 VALU per iteration removed from the load sections
# baseline (speedup 1.0000x reference)
; #define PG8_STAGE(bufoff, gbase, voff) do { _Pragma("unroll") for (int _i = 0; _i < 2; ++_i) \
;         __builtin_amdgcn_global_load_lds((const unsigned*)((const char*)(gbase) + (voff)[_i]), (LAS unsigned*)(lds + (bufoff) + ldsw + _i * 8192), 16, 0, 0); } while (0)
; #define PG8_LDA(dst, b, h) do { _Pragma("unroll") for (int m = 0; m < 4; ++m) _Pragma("unroll") for (int k = 0; k < 2; ++k) dst[m][k] = *(const LAS bf16x8*)(lds + PG8_SA(b, h) + aoff + m * 2048 + k * 1024); } while (0)
; #define PG8_LDB(dst, b, h) do { _Pragma("unroll") for (int n = 0; n < 2; ++n) _Pragma("unroll") for (int k = 0; k < 2; ++k) dst[n][k] = *(const LAS bf16x8*)(lds + PG8_SB(b, h) + boff + n * 2048 + k * 1024); } while (0)
; #define PG8_MMA(ai, bj, At, Bt) do { __builtin_amdgcn_s_setprio(1); _Pragma("unroll") for (int m = 0; m < 4; ++m) _Pragma("unroll") for (int n = 0; n < 2; ++n) _Pragma("unroll") for (int k = 0; k < 2; ++k) \
;         acc[ai][bj][m][n] = __builtin_amdgcn_mfma_f32_16x16x32_bf16(Bt[n][k], At[m][k], acc[ai][bj][m][n], 0, 0, 0); __builtin_amdgcn_s_setprio(0); } while (0)
; #define PG8_WAIT_V(n) asm volatile("s_waitcnt vmcnt(" #n ")" ::: "memory")
; #define PG8_WAIT_L(n) asm volatile("s_waitcnt lgkmcnt(" #n ")" ::: "memory")
; template <class Epi>
; __device__ __forceinline__ void gemm_phase(LAS unsigned char* lds, const Gemm g, const int G, const int cidx, const Epi& E) {
;     ...
;         const char* nA = has_next ? PG8_ABASE(nxt) : cA; const char* nB = has_next ? (const char*)g.Bt + (size_t)nxt.pn * tstep : cB;
;         for (int t = 0; t < nt; t += 2) {
;             const bool last = (t == nt - 2);
;             const char* a1 = cA + (size_t)(t + 1) * kstep;
;             const char* a2 = last ? nA : cA + (size_t)(t + 2) * kstep; const char* b2 = last ? nB : cB + (size_t)(t + 2) * kstep;
;             const char* a3 = a2 + kstep; const char* b3 = b2 + kstep;
;             PG8_LDB(B0, 0, 0); PG8_LDB(B1, 0, 1); PG8_SCHED; PG8_LDA(At, 0, 0); PG8_STAGE(PG8_SA(1, 1), a1 + hstep, voffA);
;             PG8_WAIT_V(8); PG8_WAIT_L(0); PG8_BAR; PG8_MMA(0, 0, At, B0); PG8_MMA(0, 1, At, B1); PG8_BAR; PG8_SCHED;
;             PG8_LDA(At, 0, 1); PG8_STAGE(PG8_SB(0, 0), b2, voffB); PG8_STAGE(PG8_SB(0, 1), b2 + hstep, voffB); PG8_STAGE(PG8_SA(0, 0), a2, voffA);
;             PG8_WAIT_V(8); PG8_WAIT_L(0); PG8_BAR; PG8_MMA(1, 0, At, B0); PG8_MMA(1, 1, At, B1); PG8_BAR; PG8_SCHED;
.LBB0_81:
	s_ashr_i32 s13, s12, 31
	v_cmp_lt_i64_e32 vcc, s[14:15], v[240:241]
	s_lshl_b64 s[14:15], s[12:13], 19
	s_add_u32 s14, s42, s14
	s_addc_u32 s15, s94, s15
	s_and_b64 s[18:19], vcc, exec
	s_cselect_b32 s13, s15, s27
	s_cselect_b32 s17, s14, s26
	s_ashr_i32 s9, s8, 31
	s_lshl_b64 s[18:19], s[8:9], 19
	s_add_u32 s18, s96, s18
	s_addc_u32 s19, s97, s19
	s_and_b64 s[28:29], vcc, exec
	s_cselect_b32 s9, s19, s25
	s_cselect_b32 s22, s18, s24
	s_add_u32 s33, s24, 0x100
	s_addc_u32 s44, s25, 0
	s_add_u32 s24, s26, 0x40080
	s_addc_u32 s25, s27, 0
	s_mov_b32 s45, -2
	s_add_u32 s26, s24, 0xfffc0080
	s_addc_u32 s27, s25, -1
	s_add_i32 s43, 0, 0x10000
	s_cmp_eq_u32 s45, 12
	s_cselect_b32 s29, s13, s27
	s_cselect_b32 s28, s17, s26
	s_cselect_b32 s27, s9, s44
	s_cselect_b32 s26, s22, s33
	s_add_i32 s68, 0, 0x14000
	v_add_u32_e32 v162, s43, v145
	v_add_u32_e32 v178, s68, v145
	ds_read_b128 v[132:135], v162
	ds_read_b128 v[140:143], v162 offset:1024
	ds_read_b128 v[156:159], v162 offset:2048
	ds_read_b128 v[162:165], v162 offset:3072
	ds_read_b128 v[166:169], v178
	ds_read_b128 v[170:173], v178 offset:1024
	ds_read_b128 v[174:177], v178 offset:2048
	ds_read_b128 v[178:181], v178 offset:3072
	s_add_i32 m0, s21, 0xc000
	ds_read_b128 v[182:185], v161
	ds_read_b128 v[186:189], v161 offset:1024
	ds_read_b128 v[190:193], v161 offset:2048
	ds_read_b128 v[194:197], v161 offset:3072
	ds_read_b128 v[198:201], v161 offset:4096
	ds_read_b128 v[214:217], v161 offset:5120
	ds_read_b128 v[218:221], v161 offset:6144
	ds_read_b128 v[222:225], v161 offset:7168
	global_load_lds_dwordx4 v154, s[24:25]
	s_add_i32 m0, s21, 0xe000
	s_nop 0
	global_load_lds_dwordx4 v152, s[24:25]
	s_waitcnt vmcnt(8)
	s_waitcnt lgkmcnt(0)
	s_barrier
	s_setprio 1
	s_waitcnt lgkmcnt(0)
	v_mfma_f32_16x16x32_bf16 v[128:131], v[132:135], v[182:185], 0
	v_mfma_f32_16x16x32_bf16 v[120:123], v[156:159], v[182:185], 0
	v_mfma_f32_16x16x32_bf16 v[112:115], v[132:135], v[190:193], 0
	v_mfma_f32_16x16x32_bf16 v[104:107], v[156:159], v[190:193], 0
	v_mfma_f32_16x16x32_bf16 v[96:99], v[132:135], v[198:201], 0
	v_mfma_f32_16x16x32_bf16 v[88:91], v[156:159], v[198:201], 0
	v_mfma_f32_16x16x32_bf16 v[80:83], v[132:135], v[218:221], 0
	v_mfma_f32_16x16x32_bf16 v[72:75], v[156:159], v[218:221], 0
	v_mfma_f32_16x16x32_bf16 v[128:131], v[140:143], v[186:189], v[128:131]
	v_mfma_f32_16x16x32_bf16 v[120:123], v[162:165], v[186:189], v[120:123]
	v_mfma_f32_16x16x32_bf16 v[112:115], v[140:143], v[194:197], v[112:115]
	v_mfma_f32_16x16x32_bf16 v[104:107], v[162:165], v[194:197], v[104:107]
	v_mfma_f32_16x16x32_bf16 v[96:99], v[140:143], v[214:217], v[96:99]
	v_mfma_f32_16x16x32_bf16 v[88:91], v[162:165], v[214:217], v[88:91]
	v_mfma_f32_16x16x32_bf16 v[80:83], v[140:143], v[222:225], v[80:83]
	v_mfma_f32_16x16x32_bf16 v[72:75], v[162:165], v[222:225], v[72:75]
	s_setprio 0
	s_setprio 1
	v_mfma_f32_16x16x32_bf16 v[124:127], v[166:169], v[182:185], 0
	v_mfma_f32_16x16x32_bf16 v[116:119], v[174:177], v[182:185], 0
	v_mfma_f32_16x16x32_bf16 v[108:111], v[166:169], v[190:193], 0
	v_mfma_f32_16x16x32_bf16 v[100:103], v[174:177], v[190:193], 0
	v_mfma_f32_16x16x32_bf16 v[92:95], v[166:169], v[198:201], 0
	v_mfma_f32_16x16x32_bf16 v[84:87], v[174:177], v[198:201], 0
	v_mfma_f32_16x16x32_bf16 v[76:79], v[166:169], v[218:221], 0
	v_mfma_f32_16x16x32_bf16 v[68:71], v[174:177], v[218:221], 0
	v_mfma_f32_16x16x32_bf16 v[124:127], v[170:173], v[186:189], v[124:127]
	v_mfma_f32_16x16x32_bf16 v[116:119], v[178:181], v[186:189], v[116:119]
	v_mfma_f32_16x16x32_bf16 v[108:111], v[170:173], v[194:197], v[108:111]
	v_mfma_f32_16x16x32_bf16 v[100:103], v[178:181], v[194:197], v[100:103]
	v_mfma_f32_16x16x32_bf16 v[92:95], v[170:173], v[214:217], v[92:95]
	v_mfma_f32_16x16x32_bf16 v[84:87], v[178:181], v[214:217], v[84:87]
	v_mfma_f32_16x16x32_bf16 v[76:79], v[170:173], v[222:225], v[76:79]
	v_mfma_f32_16x16x32_bf16 v[68:71], v[178:181], v[222:225], v[68:71]
	s_setprio 0
	s_barrier
	s_add_i32 s43, s43, s36
	s_mov_b32 m0, s43
	ds_read_b128 v[182:185], v161 offset:16384
	ds_read_b128 v[186:189], v161 offset:17408
	ds_read_b128 v[190:193], v161 offset:18432
	ds_read_b128 v[194:197], v161 offset:19456
	ds_read_b128 v[198:201], v161 offset:20480
	ds_read_b128 v[214:217], v161 offset:21504
	ds_read_b128 v[218:221], v161 offset:22528
	ds_read_b128 v[222:225], v161 offset:23552
	global_load_lds_dwordx4 v148, s[26:27]
	s_add_i32 m0, s43, 0x2000
	s_add_u32 s76, s26, 0x40000
	s_addc_u32 s77, s27, 0
	s_add_i32 s43, s68, s36
	global_load_lds_dwordx4 v0, s[26:27]
	s_mov_b32 m0, s43
	s_nop 0
	global_load_lds_dwordx4 v148, s[76:77]
	s_add_i32 m0, s43, 0x2000
	s_nop 0
	global_load_lds_dwordx4 v0, s[76:77]
	s_mov_b32 m0, s21
	s_nop 0
	global_load_lds_dwordx4 v150, s[28:29]
	s_mov_b32 m0, s38
	s_nop 0
	global_load_lds_dwordx4 v146, s[28:29]
	s_waitcnt vmcnt(8)
	s_waitcnt lgkmcnt(0)
	s_barrier
; #define PG8_STAGE(bufoff, gbase, voff) do { _Pragma("unroll") for (int _i = 0; _i < 2; ++_i) \
;         __builtin_amdgcn_global_load_lds((const unsigned*)((const char*)(gbase) + (voff)[_i]), (LAS unsigned*)(lds + (bufoff) + ldsw + _i * 8192), 16, 0, 0); } while (0)
; #define PG8_LDA(dst, b, h) do { _Pragma("unroll") for (int m = 0; m < 4; ++m) _Pragma("unroll") for (int k = 0; k < 2; ++k) dst[m][k] = *(const LAS bf16x8*)(lds + PG8_SA(b, h) + aoff + m * 2048 + k * 1024); } while (0)
; #define PG8_LDB(dst, b, h) do { _Pragma("unroll") for (int n = 0; n < 2; ++n) _Pragma("unroll") for (int k = 0; k < 2; ++k) dst[n][k] = *(const LAS bf16x8*)(lds + PG8_SB(b, h) + boff + n * 2048 + k * 1024); } while (0)
; #define PG8_MMA(ai, bj, At, Bt) do { __builtin_amdgcn_s_setprio(1); _Pragma("unroll") for (int m = 0; m < 4; ++m) _Pragma("unroll") for (int n = 0; n < 2; ++n) _Pragma("unroll") for (int k = 0; k < 2; ++k) \
;         acc[ai][bj][m][n] = __builtin_amdgcn_mfma_f32_16x16x32_bf16(Bt[n][k], At[m][k], acc[ai][bj][m][n], 0, 0, 0); __builtin_amdgcn_s_setprio(0); } while (0)
; #define PG8_WAIT_V(n) asm volatile("s_waitcnt vmcnt(" #n ")" ::: "memory")
; #define PG8_WAIT_L(n) asm volatile("s_waitcnt lgkmcnt(" #n ")" ::: "memory")
; #define PG8_BAR __builtin_amdgcn_s_barrier()
; #define PG8_SCHED __builtin_amdgcn_sched_barrier(0)
; template <class Epi>
; __device__ __forceinline__ void gemm_phase(LAS unsigned char* lds, const Gemm g, const int G, const int cidx, const Epi& E) {
;     ...
;             PG8_LDA(At, 0, 1); PG8_STAGE(PG8_SB(0, 0), b2, voffB); PG8_STAGE(PG8_SB(0, 1), b2 + hstep, voffB); PG8_STAGE(PG8_SA(0, 0), a2, voffA);
;             PG8_WAIT_V(8); PG8_WAIT_L(0); PG8_BAR; PG8_MMA(1, 0, At, B0); PG8_MMA(1, 1, At, B1); PG8_BAR; PG8_SCHED;
;             PG8_LDB(B0, 1, 0); PG8_LDB(B1, 1, 1); PG8_SCHED; PG8_LDA(At, 1, 0); PG8_STAGE(PG8_SA(0, 1), a2 + hstep, voffA);
;             PG8_WAIT_V(8); PG8_WAIT_L(0); PG8_BAR; PG8_MMA(0, 0, At, B0); PG8_MMA(0, 1, At, B1); PG8_BAR; PG8_SCHED;
;             PG8_LDA(At, 1, 1); PG8_STAGE(PG8_SB(1, 0), b3, voffB); PG8_STAGE(PG8_SB(1, 1), b3 + hstep, voffB); PG8_STAGE(PG8_SA(1, 0), a3, voffA);
;             PG8_WAIT_V(8); PG8_WAIT_L(0); PG8_BAR; PG8_MMA(1, 0, At, B0); PG8_MMA(1, 1, At, B1); PG8_BAR; PG8_SCHED;
	s_setprio 1
	s_waitcnt lgkmcnt(0)
	v_mfma_f32_16x16x32_bf16 v[64:67], v[132:135], v[182:185], 0
	v_mfma_f32_16x16x32_bf16 v[56:59], v[156:159], v[182:185], 0
	v_mfma_f32_16x16x32_bf16 v[48:51], v[132:135], v[190:193], 0
	v_mfma_f32_16x16x32_bf16 v[40:43], v[156:159], v[190:193], 0
	v_mfma_f32_16x16x32_bf16 v[32:35], v[132:135], v[198:201], 0
	v_mfma_f32_16x16x32_bf16 v[24:27], v[156:159], v[198:201], 0
	v_mfma_f32_16x16x32_bf16 v[16:19], v[132:135], v[218:221], 0
	v_mfma_f32_16x16x32_bf16 v[8:11], v[156:159], v[218:221], 0
	v_mfma_f32_16x16x32_bf16 v[64:67], v[140:143], v[186:189], v[64:67]
	v_mfma_f32_16x16x32_bf16 v[56:59], v[162:165], v[186:189], v[56:59]
	v_mfma_f32_16x16x32_bf16 v[48:51], v[140:143], v[194:197], v[48:51]
	v_mfma_f32_16x16x32_bf16 v[40:43], v[162:165], v[194:197], v[40:43]
	v_mfma_f32_16x16x32_bf16 v[32:35], v[140:143], v[214:217], v[32:35]
	v_mfma_f32_16x16x32_bf16 v[24:27], v[162:165], v[214:217], v[24:27]
	v_mfma_f32_16x16x32_bf16 v[16:19], v[140:143], v[222:225], v[16:19]
	v_mfma_f32_16x16x32_bf16 v[8:11], v[162:165], v[222:225], v[8:11]
	s_setprio 0
	s_setprio 1
	v_mfma_f32_16x16x32_bf16 v[60:63], v[166:169], v[182:185], 0
	v_mfma_f32_16x16x32_bf16 v[52:55], v[174:177], v[182:185], 0
	v_mfma_f32_16x16x32_bf16 v[44:47], v[166:169], v[190:193], 0
	v_mfma_f32_16x16x32_bf16 v[36:39], v[174:177], v[190:193], 0
	v_mfma_f32_16x16x32_bf16 v[28:31], v[166:169], v[198:201], 0
	v_mfma_f32_16x16x32_bf16 v[20:23], v[174:177], v[198:201], 0
	v_mfma_f32_16x16x32_bf16 v[12:15], v[166:169], v[218:221], 0
	v_mfma_f32_16x16x32_bf16 v[4:7], v[174:177], v[218:221], 0
	v_mfma_f32_16x16x32_bf16 v[60:63], v[170:173], v[186:189], v[60:63]
	v_mfma_f32_16x16x32_bf16 v[52:55], v[178:181], v[186:189], v[52:55]
	v_mfma_f32_16x16x32_bf16 v[44:47], v[170:173], v[194:197], v[44:47]
	v_mfma_f32_16x16x32_bf16 v[36:39], v[178:181], v[194:197], v[36:39]
	v_mfma_f32_16x16x32_bf16 v[28:31], v[170:173], v[214:217], v[28:31]
	v_mfma_f32_16x16x32_bf16 v[20:23], v[178:181], v[214:217], v[20:23]
	v_mfma_f32_16x16x32_bf16 v[12:15], v[170:173], v[222:225], v[12:15]
	v_mfma_f32_16x16x32_bf16 v[4:7], v[178:181], v[222:225], v[4:7]
	s_setprio 0
	s_barrier
	s_add_i32 s43, 0, 0x18000
	s_add_i32 s68, 0, 0x1c000
	v_add_u32_e32 v162, s43, v145
	v_add_u32_e32 v178, s68, v145
	ds_read_b128 v[132:135], v162
	ds_read_b128 v[140:143], v162 offset:1024
	ds_read_b128 v[156:159], v162 offset:2048
	ds_read_b128 v[162:165], v162 offset:3072
	ds_read_b128 v[166:169], v178
	ds_read_b128 v[170:173], v178 offset:1024
	ds_read_b128 v[174:177], v178 offset:2048
	ds_read_b128 v[178:181], v178 offset:3072
	s_add_u32 s98, s28, 0x80
	s_addc_u32 s99, s29, 0
	s_add_u32 s28, s28, 0x40000
	s_addc_u32 s29, s29, 0
	s_mov_b32 m0, s39
	ds_read_b128 v[182:185], v161 offset:32768
	ds_read_b128 v[186:189], v161 offset:33792
	ds_read_b128 v[190:193], v161 offset:34816
	ds_read_b128 v[194:197], v161 offset:35840
	ds_read_b128 v[198:201], v161 offset:36864
	ds_read_b128 v[214:217], v161 offset:37888
	ds_read_b128 v[218:221], v161 offset:38912
	ds_read_b128 v[222:225], v161 offset:39936
	global_load_lds_dwordx4 v150, s[28:29]
	s_mov_b32 m0, s75
	s_nop 0
	global_load_lds_dwordx4 v146, s[28:29]
	s_waitcnt vmcnt(8)
	s_waitcnt lgkmcnt(0)
	s_barrier
	s_setprio 1
	s_waitcnt lgkmcnt(0)
	v_mfma_f32_16x16x32_bf16 v[128:131], v[132:135], v[182:185], v[128:131]
	v_mfma_f32_16x16x32_bf16 v[120:123], v[156:159], v[182:185], v[120:123]
	v_mfma_f32_16x16x32_bf16 v[112:115], v[132:135], v[190:193], v[112:115]
	v_mfma_f32_16x16x32_bf16 v[104:107], v[156:159], v[190:193], v[104:107]
	v_mfma_f32_16x16x32_bf16 v[96:99], v[132:135], v[198:201], v[96:99]
	v_mfma_f32_16x16x32_bf16 v[88:91], v[156:159], v[198:201], v[88:91]
	v_mfma_f32_16x16x32_bf16 v[80:83], v[132:135], v[218:221], v[80:83]
	v_mfma_f32_16x16x32_bf16 v[72:75], v[156:159], v[218:221], v[72:75]
	v_mfma_f32_16x16x32_bf16 v[128:131], v[140:143], v[186:189], v[128:131]
	v_mfma_f32_16x16x32_bf16 v[120:123], v[162:165], v[186:189], v[120:123]
	v_mfma_f32_16x16x32_bf16 v[112:115], v[140:143], v[194:197], v[112:115]
	v_mfma_f32_16x16x32_bf16 v[104:107], v[162:165], v[194:197], v[104:107]
	v_mfma_f32_16x16x32_bf16 v[96:99], v[140:143], v[214:217], v[96:99]
	v_mfma_f32_16x16x32_bf16 v[88:91], v[162:165], v[214:217], v[88:91]
	v_mfma_f32_16x16x32_bf16 v[80:83], v[140:143], v[222:225], v[80:83]
	v_mfma_f32_16x16x32_bf16 v[72:75], v[162:165], v[222:225], v[72:75]
	s_setprio 0
	s_setprio 1
	v_mfma_f32_16x16x32_bf16 v[124:127], v[166:169], v[182:185], v[124:127]
	v_mfma_f32_16x16x32_bf16 v[116:119], v[174:177], v[182:185], v[116:119]
	v_mfma_f32_16x16x32_bf16 v[108:111], v[166:169], v[190:193], v[108:111]
	v_mfma_f32_16x16x32_bf16 v[100:103], v[174:177], v[190:193], v[100:103]
	v_mfma_f32_16x16x32_bf16 v[92:95], v[166:169], v[198:201], v[92:95]
	v_mfma_f32_16x16x32_bf16 v[84:87], v[174:177], v[198:201], v[84:87]
	v_mfma_f32_16x16x32_bf16 v[76:79], v[166:169], v[218:221], v[76:79]
	v_mfma_f32_16x16x32_bf16 v[68:71], v[174:177], v[218:221], v[68:71]
	v_mfma_f32_16x16x32_bf16 v[124:127], v[170:173], v[186:189], v[124:127]
	v_mfma_f32_16x16x32_bf16 v[116:119], v[178:181], v[186:189], v[116:119]
	v_mfma_f32_16x16x32_bf16 v[108:111], v[170:173], v[194:197], v[108:111]
	v_mfma_f32_16x16x32_bf16 v[100:103], v[178:181], v[194:197], v[100:103]
	v_mfma_f32_16x16x32_bf16 v[92:95], v[170:173], v[214:217], v[92:95]
	v_mfma_f32_16x16x32_bf16 v[84:87], v[178:181], v[214:217], v[84:87]
	v_mfma_f32_16x16x32_bf16 v[76:79], v[170:173], v[222:225], v[76:79]
	v_mfma_f32_16x16x32_bf16 v[68:71], v[178:181], v[222:225], v[68:71]
	s_setprio 0
	s_barrier
; #define PG8_STAGE(bufoff, gbase, voff) do { _Pragma("unroll") for (int _i = 0; _i < 2; ++_i) \
;         __builtin_amdgcn_global_load_lds((const unsigned*)((const char*)(gbase) + (voff)[_i]), (LAS unsigned*)(lds + (bufoff) + ldsw + _i * 8192), 16, 0, 0); } while (0)
; #define PG8_LDA(dst, b, h) do { _Pragma("unroll") for (int m = 0; m < 4; ++m) _Pragma("unroll") for (int k = 0; k < 2; ++k) dst[m][k] = *(const LAS bf16x8*)(lds + PG8_SA(b, h) + aoff + m * 2048 + k * 1024); } while (0)
; #define PG8_LDB(dst, b, h) do { _Pragma("unroll") for (int n = 0; n < 2; ++n) _Pragma("unroll") for (int k = 0; k < 2; ++k) dst[n][k] = *(const LAS bf16x8*)(lds + PG8_SB(b, h) + boff + n * 2048 + k * 1024); } while (0)
; #define PG8_WAIT_V(n) asm volatile("s_waitcnt vmcnt(" #n ")" ::: "memory")
; #define PG8_WAIT_L(n) asm volatile("s_waitcnt lgkmcnt(" #n ")" ::: "memory")
; template <class Epi>
; __device__ __forceinline__ void gemm_phase(LAS unsigned char* lds, const Gemm g, const int G, const int cidx, const Epi& E) {
;     ...
;         for (int t = 0; t < nt; t += 2) {
;             const bool last = (t == nt - 2);
;             const char* a1 = cA + (size_t)(t + 1) * kstep;
;             const char* a2 = last ? nA : cA + (size_t)(t + 2) * kstep; const char* b2 = last ? nB : cB + (size_t)(t + 2) * kstep;
;             const char* a3 = a2 + kstep; const char* b3 = b2 + kstep;
;             PG8_LDB(B0, 0, 0); PG8_LDB(B1, 0, 1); PG8_SCHED; PG8_LDA(At, 0, 0); PG8_STAGE(PG8_SA(1, 1), a1 + hstep, voffA);
;             PG8_WAIT_V(8); PG8_WAIT_L(0); PG8_BAR; PG8_MMA(0, 0, At, B0); PG8_MMA(0, 1, At, B1); PG8_BAR; PG8_SCHED;
;             PG8_LDA(At, 0, 1); PG8_STAGE(PG8_SB(0, 0), b2, voffB); PG8_STAGE(PG8_SB(0, 1), b2 + hstep, voffB); PG8_STAGE(PG8_SA(0, 0), a2, voffA);
;             PG8_WAIT_V(8); PG8_WAIT_L(0); PG8_BAR; PG8_MMA(1, 0, At, B0); PG8_MMA(1, 1, At, B1); PG8_BAR; PG8_SCHED;
;             PG8_LDB(B0, 1, 0); PG8_LDB(B1, 1, 1); PG8_SCHED; PG8_LDA(At, 1, 0); PG8_STAGE(PG8_SA(0, 1), a2 + hstep, voffA);
;             PG8_WAIT_V(8); PG8_WAIT_L(0); PG8_BAR; PG8_MMA(0, 0, At, B0); PG8_MMA(0, 1, At, B1); PG8_BAR; PG8_SCHED;
;             PG8_LDA(At, 1, 1); PG8_STAGE(PG8_SB(1, 0), b3, voffB); PG8_STAGE(PG8_SB(1, 1), b3 + hstep, voffB); PG8_STAGE(PG8_SA(1, 0), a3, voffA);
;             PG8_WAIT_V(8); PG8_WAIT_L(0); PG8_BAR; PG8_MMA(1, 0, At, B0); PG8_MMA(1, 1, At, B1); PG8_BAR; PG8_SCHED;
	s_add_i32 s28, s43, s36
	s_add_u32 s100, s26, 0x80
	s_addc_u32 s101, s27, 0
	s_mov_b32 m0, s28
	ds_read_b128 v[182:185], v161 offset:49152
	ds_read_b128 v[186:189], v161 offset:50176
	ds_read_b128 v[190:193], v161 offset:51200
	ds_read_b128 v[194:197], v161 offset:52224
	ds_read_b128 v[198:201], v161 offset:53248
	ds_read_b128 v[214:217], v161 offset:54272
	ds_read_b128 v[218:221], v161 offset:55296
	ds_read_b128 v[222:225], v161 offset:56320
	global_load_lds_dwordx4 v148, s[100:101]
	s_add_i32 m0, s28, 0x2000
	s_add_i32 s28, s68, s36
	global_load_lds_dwordx4 v0, s[100:101]
	s_add_u32 s100, s100, 0x40000
	s_addc_u32 s101, s101, 0
	s_mov_b32 m0, s28
	s_nop 0
	global_load_lds_dwordx4 v148, s[100:101]
	s_add_i32 m0, s28, 0x2000
	s_nop 0
	global_load_lds_dwordx4 v0, s[100:101]
	s_mov_b32 m0, s79
	s_nop 0
	global_load_lds_dwordx4 v150, s[98:99]
	s_mov_b32 m0, s34
	s_nop 0
	global_load_lds_dwordx4 v146, s[98:99]
	s_waitcnt vmcnt(8)
	s_waitcnt lgkmcnt(0)
	s_barrier
	s_setprio 1
	s_waitcnt lgkmcnt(0)
	v_mfma_f32_16x16x32_bf16 v[64:67], v[132:135], v[182:185], v[64:67]
	v_mfma_f32_16x16x32_bf16 v[56:59], v[156:159], v[182:185], v[56:59]
	v_mfma_f32_16x16x32_bf16 v[48:51], v[132:135], v[190:193], v[48:51]
	v_mfma_f32_16x16x32_bf16 v[40:43], v[156:159], v[190:193], v[40:43]
	v_mfma_f32_16x16x32_bf16 v[32:35], v[132:135], v[198:201], v[32:35]
	v_mfma_f32_16x16x32_bf16 v[24:27], v[156:159], v[198:201], v[24:27]
	v_mfma_f32_16x16x32_bf16 v[16:19], v[132:135], v[218:221], v[16:19]
	v_mfma_f32_16x16x32_bf16 v[8:11], v[156:159], v[218:221], v[8:11]
	v_mfma_f32_16x16x32_bf16 v[64:67], v[140:143], v[186:189], v[64:67]
	v_mfma_f32_16x16x32_bf16 v[56:59], v[162:165], v[186:189], v[56:59]
	v_mfma_f32_16x16x32_bf16 v[48:51], v[140:143], v[194:197], v[48:51]
	v_mfma_f32_16x16x32_bf16 v[40:43], v[162:165], v[194:197], v[40:43]
	v_mfma_f32_16x16x32_bf16 v[32:35], v[140:143], v[214:217], v[32:35]
	v_mfma_f32_16x16x32_bf16 v[24:27], v[162:165], v[214:217], v[24:27]
	v_mfma_f32_16x16x32_bf16 v[16:19], v[140:143], v[222:225], v[16:19]
	v_mfma_f32_16x16x32_bf16 v[8:11], v[162:165], v[222:225], v[8:11]
	s_setprio 0
	s_setprio 1
	v_mfma_f32_16x16x32_bf16 v[60:63], v[166:169], v[182:185], v[60:63]
	v_mfma_f32_16x16x32_bf16 v[52:55], v[174:177], v[182:185], v[52:55]
	v_mfma_f32_16x16x32_bf16 v[44:47], v[166:169], v[190:193], v[44:47]
	v_mfma_f32_16x16x32_bf16 v[36:39], v[174:177], v[190:193], v[36:39]
	v_mfma_f32_16x16x32_bf16 v[28:31], v[166:169], v[198:201], v[28:31]
	v_mfma_f32_16x16x32_bf16 v[20:23], v[174:177], v[198:201], v[20:23]
	v_mfma_f32_16x16x32_bf16 v[12:15], v[166:169], v[218:221], v[12:15]
	v_mfma_f32_16x16x32_bf16 v[4:7], v[174:177], v[218:221], v[4:7]
	v_mfma_f32_16x16x32_bf16 v[60:63], v[170:173], v[186:189], v[60:63]
	v_mfma_f32_16x16x32_bf16 v[52:55], v[178:181], v[186:189], v[52:55]
	v_mfma_f32_16x16x32_bf16 v[44:47], v[170:173], v[194:197], v[44:47]
	v_mfma_f32_16x16x32_bf16 v[36:39], v[178:181], v[194:197], v[36:39]
	v_mfma_f32_16x16x32_bf16 v[28:31], v[170:173], v[214:217], v[28:31]
	v_mfma_f32_16x16x32_bf16 v[20:23], v[178:181], v[214:217], v[20:23]
	v_mfma_f32_16x16x32_bf16 v[12:15], v[170:173], v[222:225], v[12:15]
	v_mfma_f32_16x16x32_bf16 v[4:7], v[178:181], v[222:225], v[4:7]
	s_setprio 0
	s_barrier
	s_add_i32 s45, s45, 2
	s_add_u32 s33, s33, 0x100
	s_addc_u32 s44, s44, 0
	s_add_u32 s24, s24, 0x100
	s_addc_u32 s25, s25, 0
.LBB0_82:
	s_add_u32 s26, s24, 0xfffc0080
	s_addc_u32 s27, s25, -1
	s_add_i32 s43, 0, 0x10000
	s_cmp_eq_u32 s45, 12
	s_cselect_b32 s29, s13, s27
	s_cselect_b32 s28, s17, s26
	s_cselect_b32 s27, s9, s44
	s_cselect_b32 s26, s22, s33
	s_add_i32 s68, 0, 0x14000
	v_add_u32_e32 v162, s43, v145
	v_add_u32_e32 v178, s68, v145
	ds_read_b128 v[132:135], v162
	ds_read_b128 v[140:143], v162 offset:1024
	ds_read_b128 v[156:159], v162 offset:2048
	ds_read_b128 v[162:165], v162 offset:3072
	ds_read_b128 v[166:169], v178
	ds_read_b128 v[170:173], v178 offset:1024
	ds_read_b128 v[174:177], v178 offset:2048
	ds_read_b128 v[178:181], v178 offset:3072
	s_add_i32 m0, s21, 0xc000
	ds_read_b128 v[182:185], v161
	ds_read_b128 v[186:189], v161 offset:1024
	ds_read_b128 v[190:193], v161 offset:2048
	ds_read_b128 v[194:197], v161 offset:3072
	ds_read_b128 v[198:201], v161 offset:4096
	ds_read_b128 v[214:217], v161 offset:5120
	ds_read_b128 v[218:221], v161 offset:6144
	ds_read_b128 v[222:225], v161 offset:7168
	global_load_lds_dwordx4 v154, s[24:25]
	s_add_i32 m0, s21, 0xe000
	s_nop 0
	global_load_lds_dwordx4 v152, s[24:25]
	s_waitcnt vmcnt(8)
	s_waitcnt lgkmcnt(0)
	s_barrier
; #define PG8_STAGE(bufoff, gbase, voff) do { _Pragma("unroll") for (int _i = 0; _i < 2; ++_i) \
;         __builtin_amdgcn_global_load_lds((const unsigned*)((const char*)(gbase) + (voff)[_i]), (LAS unsigned*)(lds + (bufoff) + ldsw + _i * 8192), 16, 0, 0); } while (0)
; #define PG8_LDA(dst, b, h) do { _Pragma("unroll") for (int m = 0; m < 4; ++m) _Pragma("unroll") for (int k = 0; k < 2; ++k) dst[m][k] = *(const LAS bf16x8*)(lds + PG8_SA(b, h) + aoff + m * 2048 + k * 1024); } while (0)
; #define PG8_LDB(dst, b, h) do { _Pragma("unroll") for (int n = 0; n < 2; ++n) _Pragma("unroll") for (int k = 0; k < 2; ++k) dst[n][k] = *(const LAS bf16x8*)(lds + PG8_SB(b, h) + boff + n * 2048 + k * 1024); } while (0)
; #define PG8_MMA(ai, bj, At, Bt) do { __builtin_amdgcn_s_setprio(1); _Pragma("unroll") for (int m = 0; m < 4; ++m) _Pragma("unroll") for (int n = 0; n < 2; ++n) _Pragma("unroll") for (int k = 0; k < 2; ++k) \
;         acc[ai][bj][m][n] = __builtin_amdgcn_mfma_f32_16x16x32_bf16(Bt[n][k], At[m][k], acc[ai][bj][m][n], 0, 0, 0); __builtin_amdgcn_s_setprio(0); } while (0)
; #define PG8_WAIT_V(n) asm volatile("s_waitcnt vmcnt(" #n ")" ::: "memory")
; #define PG8_WAIT_L(n) asm volatile("s_waitcnt lgkmcnt(" #n ")" ::: "memory")
; #define PG8_BAR __builtin_amdgcn_s_barrier()
; #define PG8_SCHED __builtin_amdgcn_sched_barrier(0)
; template <class Epi>
; __device__ __forceinline__ void gemm_phase(LAS unsigned char* lds, const Gemm g, const int G, const int cidx, const Epi& E) {
;     ...
;             PG8_LDB(B0, 0, 0); PG8_LDB(B1, 0, 1); PG8_SCHED; PG8_LDA(At, 0, 0); PG8_STAGE(PG8_SA(1, 1), a1 + hstep, voffA);
;             PG8_WAIT_V(8); PG8_WAIT_L(0); PG8_BAR; PG8_MMA(0, 0, At, B0); PG8_MMA(0, 1, At, B1); PG8_BAR; PG8_SCHED;
;             PG8_LDA(At, 0, 1); PG8_STAGE(PG8_SB(0, 0), b2, voffB); PG8_STAGE(PG8_SB(0, 1), b2 + hstep, voffB); PG8_STAGE(PG8_SA(0, 0), a2, voffA);
;             PG8_WAIT_V(8); PG8_WAIT_L(0); PG8_BAR; PG8_MMA(1, 0, At, B0); PG8_MMA(1, 1, At, B1); PG8_BAR; PG8_SCHED;
	s_setprio 1
	s_waitcnt lgkmcnt(0)
	v_mfma_f32_16x16x32_bf16 v[128:131], v[132:135], v[182:185], v[128:131]
	v_mfma_f32_16x16x32_bf16 v[120:123], v[156:159], v[182:185], v[120:123]
	v_mfma_f32_16x16x32_bf16 v[112:115], v[132:135], v[190:193], v[112:115]
	v_mfma_f32_16x16x32_bf16 v[104:107], v[156:159], v[190:193], v[104:107]
	v_mfma_f32_16x16x32_bf16 v[96:99], v[132:135], v[198:201], v[96:99]
	v_mfma_f32_16x16x32_bf16 v[88:91], v[156:159], v[198:201], v[88:91]
	v_mfma_f32_16x16x32_bf16 v[80:83], v[132:135], v[218:221], v[80:83]
	v_mfma_f32_16x16x32_bf16 v[72:75], v[156:159], v[218:221], v[72:75]
	v_mfma_f32_16x16x32_bf16 v[128:131], v[140:143], v[186:189], v[128:131]
	v_mfma_f32_16x16x32_bf16 v[120:123], v[162:165], v[186:189], v[120:123]
	v_mfma_f32_16x16x32_bf16 v[112:115], v[140:143], v[194:197], v[112:115]
	v_mfma_f32_16x16x32_bf16 v[104:107], v[162:165], v[194:197], v[104:107]
	v_mfma_f32_16x16x32_bf16 v[96:99], v[140:143], v[214:217], v[96:99]
	v_mfma_f32_16x16x32_bf16 v[88:91], v[162:165], v[214:217], v[88:91]
	v_mfma_f32_16x16x32_bf16 v[80:83], v[140:143], v[222:225], v[80:83]
	v_mfma_f32_16x16x32_bf16 v[72:75], v[162:165], v[222:225], v[72:75]
	s_setprio 0
	s_setprio 1
	v_mfma_f32_16x16x32_bf16 v[124:127], v[166:169], v[182:185], v[124:127]
	v_mfma_f32_16x16x32_bf16 v[116:119], v[174:177], v[182:185], v[116:119]
	v_mfma_f32_16x16x32_bf16 v[108:111], v[166:169], v[190:193], v[108:111]
	v_mfma_f32_16x16x32_bf16 v[100:103], v[174:177], v[190:193], v[100:103]
	v_mfma_f32_16x16x32_bf16 v[92:95], v[166:169], v[198:201], v[92:95]
	v_mfma_f32_16x16x32_bf16 v[84:87], v[174:177], v[198:201], v[84:87]
	v_mfma_f32_16x16x32_bf16 v[76:79], v[166:169], v[218:221], v[76:79]
	v_mfma_f32_16x16x32_bf16 v[68:71], v[174:177], v[218:221], v[68:71]
	v_mfma_f32_16x16x32_bf16 v[124:127], v[170:173], v[186:189], v[124:127]
	v_mfma_f32_16x16x32_bf16 v[116:119], v[178:181], v[186:189], v[116:119]
	v_mfma_f32_16x16x32_bf16 v[108:111], v[170:173], v[194:197], v[108:111]
	v_mfma_f32_16x16x32_bf16 v[100:103], v[178:181], v[194:197], v[100:103]
	v_mfma_f32_16x16x32_bf16 v[92:95], v[170:173], v[214:217], v[92:95]
	v_mfma_f32_16x16x32_bf16 v[84:87], v[178:181], v[214:217], v[84:87]
	v_mfma_f32_16x16x32_bf16 v[76:79], v[170:173], v[222:225], v[76:79]
	v_mfma_f32_16x16x32_bf16 v[68:71], v[178:181], v[222:225], v[68:71]
	s_setprio 0
	s_barrier
	s_add_i32 s43, s43, s36
	s_mov_b32 m0, s43
	ds_read_b128 v[182:185], v161 offset:16384
	ds_read_b128 v[186:189], v161 offset:17408
	ds_read_b128 v[190:193], v161 offset:18432
	ds_read_b128 v[194:197], v161 offset:19456
	ds_read_b128 v[198:201], v161 offset:20480
	ds_read_b128 v[214:217], v161 offset:21504
	ds_read_b128 v[218:221], v161 offset:22528
	ds_read_b128 v[222:225], v161 offset:23552
	global_load_lds_dwordx4 v148, s[26:27]
	s_add_i32 m0, s43, 0x2000
	s_add_u32 s76, s26, 0x40000
	s_addc_u32 s77, s27, 0
	s_add_i32 s43, s68, s36
	global_load_lds_dwordx4 v0, s[26:27]
	s_mov_b32 m0, s43
	s_nop 0
	global_load_lds_dwordx4 v148, s[76:77]
	s_add_i32 m0, s43, 0x2000
	s_nop 0
	global_load_lds_dwordx4 v0, s[76:77]
	s_mov_b32 m0, s21
	s_nop 0
	global_load_lds_dwordx4 v150, s[28:29]
	s_mov_b32 m0, s38
	s_nop 0
	global_load_lds_dwordx4 v146, s[28:29]
	s_waitcnt vmcnt(8)
	s_waitcnt lgkmcnt(0)
	s_barrier
	s_setprio 1
	s_waitcnt lgkmcnt(0)
	v_mfma_f32_16x16x32_bf16 v[64:67], v[132:135], v[182:185], v[64:67]
	v_mfma_f32_16x16x32_bf16 v[56:59], v[156:159], v[182:185], v[56:59]
	v_mfma_f32_16x16x32_bf16 v[48:51], v[132:135], v[190:193], v[48:51]
	v_mfma_f32_16x16x32_bf16 v[40:43], v[156:159], v[190:193], v[40:43]
	v_mfma_f32_16x16x32_bf16 v[32:35], v[132:135], v[198:201], v[32:35]
	v_mfma_f32_16x16x32_bf16 v[24:27], v[156:159], v[198:201], v[24:27]
	v_mfma_f32_16x16x32_bf16 v[16:19], v[132:135], v[218:221], v[16:19]
	v_mfma_f32_16x16x32_bf16 v[8:11], v[156:159], v[218:221], v[8:11]
	v_mfma_f32_16x16x32_bf16 v[64:67], v[140:143], v[186:189], v[64:67]
	v_mfma_f32_16x16x32_bf16 v[56:59], v[162:165], v[186:189], v[56:59]
	v_mfma_f32_16x16x32_bf16 v[48:51], v[140:143], v[194:197], v[48:51]
	v_mfma_f32_16x16x32_bf16 v[40:43], v[162:165], v[194:197], v[40:43]
	v_mfma_f32_16x16x32_bf16 v[32:35], v[140:143], v[214:217], v[32:35]
	v_mfma_f32_16x16x32_bf16 v[24:27], v[162:165], v[214:217], v[24:27]
	v_mfma_f32_16x16x32_bf16 v[16:19], v[140:143], v[222:225], v[16:19]
	v_mfma_f32_16x16x32_bf16 v[8:11], v[162:165], v[222:225], v[8:11]
	s_setprio 0
	s_setprio 1
	v_mfma_f32_16x16x32_bf16 v[60:63], v[166:169], v[182:185], v[60:63]
	v_mfma_f32_16x16x32_bf16 v[52:55], v[174:177], v[182:185], v[52:55]
	v_mfma_f32_16x16x32_bf16 v[44:47], v[166:169], v[190:193], v[44:47]
	v_mfma_f32_16x16x32_bf16 v[36:39], v[174:177], v[190:193], v[36:39]
	v_mfma_f32_16x16x32_bf16 v[28:31], v[166:169], v[198:201], v[28:31]
	v_mfma_f32_16x16x32_bf16 v[20:23], v[174:177], v[198:201], v[20:23]
	v_mfma_f32_16x16x32_bf16 v[12:15], v[166:169], v[218:221], v[12:15]
	v_mfma_f32_16x16x32_bf16 v[4:7], v[174:177], v[218:221], v[4:7]
	v_mfma_f32_16x16x32_bf16 v[60:63], v[170:173], v[186:189], v[60:63]
	v_mfma_f32_16x16x32_bf16 v[52:55], v[178:181], v[186:189], v[52:55]
	v_mfma_f32_16x16x32_bf16 v[44:47], v[170:173], v[194:197], v[44:47]
	v_mfma_f32_16x16x32_bf16 v[36:39], v[178:181], v[194:197], v[36:39]
	v_mfma_f32_16x16x32_bf16 v[28:31], v[170:173], v[214:217], v[28:31]
	v_mfma_f32_16x16x32_bf16 v[20:23], v[178:181], v[214:217], v[20:23]
	v_mfma_f32_16x16x32_bf16 v[12:15], v[170:173], v[222:225], v[12:15]
	v_mfma_f32_16x16x32_bf16 v[4:7], v[178:181], v[222:225], v[4:7]
	s_setprio 0
	s_barrier
; #define PG8_STAGE(bufoff, gbase, voff) do { _Pragma("unroll") for (int _i = 0; _i < 2; ++_i) \
;         __builtin_amdgcn_global_load_lds((const unsigned*)((const char*)(gbase) + (voff)[_i]), (LAS unsigned*)(lds + (bufoff) + ldsw + _i * 8192), 16, 0, 0); } while (0)
; #define PG8_LDA(dst, b, h) do { _Pragma("unroll") for (int m = 0; m < 4; ++m) _Pragma("unroll") for (int k = 0; k < 2; ++k) dst[m][k] = *(const LAS bf16x8*)(lds + PG8_SA(b, h) + aoff + m * 2048 + k * 1024); } while (0)
; #define PG8_LDB(dst, b, h) do { _Pragma("unroll") for (int n = 0; n < 2; ++n) _Pragma("unroll") for (int k = 0; k < 2; ++k) dst[n][k] = *(const LAS bf16x8*)(lds + PG8_SB(b, h) + boff + n * 2048 + k * 1024); } while (0)
; #define PG8_MMA(ai, bj, At, Bt) do { __builtin_amdgcn_s_setprio(1); _Pragma("unroll") for (int m = 0; m < 4; ++m) _Pragma("unroll") for (int n = 0; n < 2; ++n) _Pragma("unroll") for (int k = 0; k < 2; ++k) \
;         acc[ai][bj][m][n] = __builtin_amdgcn_mfma_f32_16x16x32_bf16(Bt[n][k], At[m][k], acc[ai][bj][m][n], 0, 0, 0); __builtin_amdgcn_s_setprio(0); } while (0)
; #define PG8_WAIT_V(n) asm volatile("s_waitcnt vmcnt(" #n ")" ::: "memory")
; #define PG8_WAIT_L(n) asm volatile("s_waitcnt lgkmcnt(" #n ")" ::: "memory")
; #define PG8_BAR __builtin_amdgcn_s_barrier()
; #define PG8_SCHED __builtin_amdgcn_sched_barrier(0)
; template <class Epi>
; __device__ __forceinline__ void gemm_phase(LAS unsigned char* lds, const Gemm g, const int G, const int cidx, const Epi& E) {
;     ...
;             PG8_LDB(B0, 1, 0); PG8_LDB(B1, 1, 1); PG8_SCHED; PG8_LDA(At, 1, 0); PG8_STAGE(PG8_SA(0, 1), a2 + hstep, voffA);
;             PG8_WAIT_V(8); PG8_WAIT_L(0); PG8_BAR; PG8_MMA(0, 0, At, B0); PG8_MMA(0, 1, At, B1); PG8_BAR; PG8_SCHED;
;             PG8_LDA(At, 1, 1); PG8_STAGE(PG8_SB(1, 0), b3, voffB); PG8_STAGE(PG8_SB(1, 1), b3 + hstep, voffB); PG8_STAGE(PG8_SA(1, 0), a3, voffA);
;             PG8_WAIT_V(8); PG8_WAIT_L(0); PG8_BAR; PG8_MMA(1, 0, At, B0); PG8_MMA(1, 1, At, B1); PG8_BAR; PG8_SCHED;
	s_add_i32 s43, 0, 0x18000
	s_add_i32 s68, 0, 0x1c000
	v_add_u32_e32 v162, s43, v145
	v_add_u32_e32 v178, s68, v145
	ds_read_b128 v[132:135], v162
	ds_read_b128 v[140:143], v162 offset:1024
	ds_read_b128 v[156:159], v162 offset:2048
	ds_read_b128 v[162:165], v162 offset:3072
	ds_read_b128 v[166:169], v178
	ds_read_b128 v[170:173], v178 offset:1024
	ds_read_b128 v[174:177], v178 offset:2048
	ds_read_b128 v[178:181], v178 offset:3072
	s_add_u32 s98, s28, 0x80
	s_addc_u32 s99, s29, 0
	s_add_u32 s28, s28, 0x40000
	s_addc_u32 s29, s29, 0
	s_mov_b32 m0, s39
	ds_read_b128 v[182:185], v161 offset:32768
	ds_read_b128 v[186:189], v161 offset:33792
	ds_read_b128 v[190:193], v161 offset:34816
	ds_read_b128 v[194:197], v161 offset:35840
	ds_read_b128 v[198:201], v161 offset:36864
	ds_read_b128 v[214:217], v161 offset:37888
	ds_read_b128 v[218:221], v161 offset:38912
	ds_read_b128 v[222:225], v161 offset:39936
	global_load_lds_dwordx4 v150, s[28:29]
	s_mov_b32 m0, s75
	s_nop 0
	global_load_lds_dwordx4 v146, s[28:29]
	s_waitcnt vmcnt(8)
	s_waitcnt lgkmcnt(0)
	s_barrier
	s_setprio 1
	s_waitcnt lgkmcnt(0)
	v_mfma_f32_16x16x32_bf16 v[128:131], v[132:135], v[182:185], v[128:131]
	v_mfma_f32_16x16x32_bf16 v[120:123], v[156:159], v[182:185], v[120:123]
	v_mfma_f32_16x16x32_bf16 v[112:115], v[132:135], v[190:193], v[112:115]
	v_mfma_f32_16x16x32_bf16 v[104:107], v[156:159], v[190:193], v[104:107]
	v_mfma_f32_16x16x32_bf16 v[96:99], v[132:135], v[198:201], v[96:99]
	v_mfma_f32_16x16x32_bf16 v[88:91], v[156:159], v[198:201], v[88:91]
	v_mfma_f32_16x16x32_bf16 v[80:83], v[132:135], v[218:221], v[80:83]
	v_mfma_f32_16x16x32_bf16 v[72:75], v[156:159], v[218:221], v[72:75]
	v_mfma_f32_16x16x32_bf16 v[128:131], v[140:143], v[186:189], v[128:131]
	v_mfma_f32_16x16x32_bf16 v[120:123], v[162:165], v[186:189], v[120:123]
	v_mfma_f32_16x16x32_bf16 v[112:115], v[140:143], v[194:197], v[112:115]
	v_mfma_f32_16x16x32_bf16 v[104:107], v[162:165], v[194:197], v[104:107]
	v_mfma_f32_16x16x32_bf16 v[96:99], v[140:143], v[214:217], v[96:99]
	v_mfma_f32_16x16x32_bf16 v[88:91], v[162:165], v[214:217], v[88:91]
	v_mfma_f32_16x16x32_bf16 v[80:83], v[140:143], v[222:225], v[80:83]
	v_mfma_f32_16x16x32_bf16 v[72:75], v[162:165], v[222:225], v[72:75]
	s_setprio 0
	s_setprio 1
	v_mfma_f32_16x16x32_bf16 v[124:127], v[166:169], v[182:185], v[124:127]
	v_mfma_f32_16x16x32_bf16 v[116:119], v[174:177], v[182:185], v[116:119]
	v_mfma_f32_16x16x32_bf16 v[108:111], v[166:169], v[190:193], v[108:111]
	v_mfma_f32_16x16x32_bf16 v[100:103], v[174:177], v[190:193], v[100:103]
	v_mfma_f32_16x16x32_bf16 v[92:95], v[166:169], v[198:201], v[92:95]
	v_mfma_f32_16x16x32_bf16 v[84:87], v[174:177], v[198:201], v[84:87]
	v_mfma_f32_16x16x32_bf16 v[76:79], v[166:169], v[218:221], v[76:79]
	v_mfma_f32_16x16x32_bf16 v[68:71], v[174:177], v[218:221], v[68:71]
	v_mfma_f32_16x16x32_bf16 v[124:127], v[170:173], v[186:189], v[124:127]
	v_mfma_f32_16x16x32_bf16 v[116:119], v[178:181], v[186:189], v[116:119]
	v_mfma_f32_16x16x32_bf16 v[108:111], v[170:173], v[194:197], v[108:111]
	v_mfma_f32_16x16x32_bf16 v[100:103], v[178:181], v[194:197], v[100:103]
	v_mfma_f32_16x16x32_bf16 v[92:95], v[170:173], v[214:217], v[92:95]
	v_mfma_f32_16x16x32_bf16 v[84:87], v[178:181], v[214:217], v[84:87]
	v_mfma_f32_16x16x32_bf16 v[76:79], v[170:173], v[222:225], v[76:79]
	v_mfma_f32_16x16x32_bf16 v[68:71], v[178:181], v[222:225], v[68:71]
	s_setprio 0
	s_barrier
	s_add_i32 s28, s43, s36
	s_add_u32 s100, s26, 0x80
	s_addc_u32 s101, s27, 0
	s_mov_b32 m0, s28
	ds_read_b128 v[182:185], v161 offset:49152
	ds_read_b128 v[186:189], v161 offset:50176
	ds_read_b128 v[190:193], v161 offset:51200
	ds_read_b128 v[194:197], v161 offset:52224
	ds_read_b128 v[198:201], v161 offset:53248
	ds_read_b128 v[214:217], v161 offset:54272
	ds_read_b128 v[218:221], v161 offset:55296
	ds_read_b128 v[222:225], v161 offset:56320
	global_load_lds_dwordx4 v148, s[100:101]
	s_add_i32 m0, s28, 0x2000
	s_add_i32 s28, s68, s36
	global_load_lds_dwordx4 v0, s[100:101]
	s_add_u32 s100, s100, 0x40000
	s_addc_u32 s101, s101, 0
	s_mov_b32 m0, s28
	s_nop 0
	global_load_lds_dwordx4 v148, s[100:101]
	s_add_i32 m0, s28, 0x2000
	s_nop 0
	global_load_lds_dwordx4 v0, s[100:101]
	s_mov_b32 m0, s79
	s_nop 0
	global_load_lds_dwordx4 v150, s[98:99]
	s_mov_b32 m0, s34
	s_nop 0
	global_load_lds_dwordx4 v146, s[98:99]
	s_waitcnt vmcnt(8)
	s_waitcnt lgkmcnt(0)
	s_barrier
	s_setprio 1
	s_waitcnt lgkmcnt(0)
	v_mfma_f32_16x16x32_bf16 v[64:67], v[132:135], v[182:185], v[64:67]
	v_mfma_f32_16x16x32_bf16 v[56:59], v[156:159], v[182:185], v[56:59]
	v_mfma_f32_16x16x32_bf16 v[48:51], v[132:135], v[190:193], v[48:51]
	v_mfma_f32_16x16x32_bf16 v[40:43], v[156:159], v[190:193], v[40:43]
	v_mfma_f32_16x16x32_bf16 v[32:35], v[132:135], v[198:201], v[32:35]
	v_mfma_f32_16x16x32_bf16 v[24:27], v[156:159], v[198:201], v[24:27]
	v_mfma_f32_16x16x32_bf16 v[16:19], v[132:135], v[218:221], v[16:19]
	v_mfma_f32_16x16x32_bf16 v[8:11], v[156:159], v[218:221], v[8:11]
	v_mfma_f32_16x16x32_bf16 v[64:67], v[140:143], v[186:189], v[64:67]
	v_mfma_f32_16x16x32_bf16 v[56:59], v[162:165], v[186:189], v[56:59]
	v_mfma_f32_16x16x32_bf16 v[48:51], v[140:143], v[194:197], v[48:51]
	v_mfma_f32_16x16x32_bf16 v[40:43], v[162:165], v[194:197], v[40:43]
	v_mfma_f32_16x16x32_bf16 v[32:35], v[140:143], v[214:217], v[32:35]
	v_mfma_f32_16x16x32_bf16 v[24:27], v[162:165], v[214:217], v[24:27]
	v_mfma_f32_16x16x32_bf16 v[16:19], v[140:143], v[222:225], v[16:19]
	v_mfma_f32_16x16x32_bf16 v[8:11], v[162:165], v[222:225], v[8:11]
	s_setprio 0
	s_setprio 1
	v_mfma_f32_16x16x32_bf16 v[60:63], v[166:169], v[182:185], v[60:63]
	v_mfma_f32_16x16x32_bf16 v[52:55], v[174:177], v[182:185], v[52:55]
	v_mfma_f32_16x16x32_bf16 v[44:47], v[166:169], v[190:193], v[44:47]
	v_mfma_f32_16x16x32_bf16 v[36:39], v[174:177], v[190:193], v[36:39]
	v_mfma_f32_16x16x32_bf16 v[28:31], v[166:169], v[198:201], v[28:31]
	v_mfma_f32_16x16x32_bf16 v[20:23], v[174:177], v[198:201], v[20:23]
	v_mfma_f32_16x16x32_bf16 v[12:15], v[166:169], v[218:221], v[12:15]
	v_mfma_f32_16x16x32_bf16 v[4:7], v[174:177], v[218:221], v[4:7]
	v_mfma_f32_16x16x32_bf16 v[60:63], v[170:173], v[186:189], v[60:63]
	v_mfma_f32_16x16x32_bf16 v[52:55], v[178:181], v[186:189], v[52:55]
	v_mfma_f32_16x16x32_bf16 v[44:47], v[170:173], v[194:197], v[44:47]
	v_mfma_f32_16x16x32_bf16 v[36:39], v[178:181], v[194:197], v[36:39]
	v_mfma_f32_16x16x32_bf16 v[28:31], v[170:173], v[214:217], v[28:31]
	v_mfma_f32_16x16x32_bf16 v[20:23], v[178:181], v[214:217], v[20:23]
	v_mfma_f32_16x16x32_bf16 v[12:15], v[170:173], v[222:225], v[12:15]
	v_mfma_f32_16x16x32_bf16 v[4:7], v[178:181], v[222:225], v[4:7]
	s_setprio 0
	s_barrier
; __device__ __forceinline__ unsigned pk2(float lo, float hi) { unsigned r; asm("v_cvt_pk_bf16_f32 %0, %1, %2" : "=v"(r) : "v"(lo), "v"(hi)); return r; }
; __device__ __forceinline__ float silu(float x) { return x * sigm(x); }
;     __device__ __forceinline__ void operator()(const f32x4 (&acc)[2][2][4][2], const Unit& u, int wr, int wc, int fr, int fq) const {
;         const int row0 = u.pm * BM + wr * 64 + fr, col0 = u.pn * HALF + wc * 32 + 8 * fq;
; #pragma unroll
;         for (int ai = 0; ai < 2; ++ai)
; #pragma unroll
;             for (int m = 0; m < 4; ++m) { bf16_t* rowp = O + (size_t)(row0 + ai * HALF + m * 16) * ldc + col0;
;                 const f32x4 g0 = acc[ai][0][m][0], g1 = acc[ai][0][m][1], u0 = acc[ai][1][m][0], u1 = acc[ai][1][m][1];
;                 u32x4 w; w.x = pk2(silu(g0[0]) * u0[0], silu(g0[1]) * u0[1]); w.y = pk2(silu(g0[2]) * u0[2], silu(g0[3]) * u0[3]);
;                 w.z = pk2(silu(g1[0]) * u1[0], silu(g1[1]) * u1[1]); w.w = pk2(silu(g1[2]) * u1[2], silu(g1[3]) * u1[3]);
;                 *(u32x4*)rowp = w; }
; template <class Epi>
; __device__ __forceinline__ void gemm_phase(LAS unsigned char* lds, const Gemm g, const int G, const int cidx, const Epi& E) {
;     ...
;         }
;         if constexpr (!Epi::AFTER_DRAIN) E(acc, cur, wr, wc, fr, fq);
;         if (!has_next) break;
	s_add_i32 s45, s45, 2
	s_add_u32 s33, s33, 0x100
	s_addc_u32 s44, s44, 0
	s_add_u32 s24, s24, 0x100
	s_addc_u32 s25, s25, 0
	s_cmp_gt_u32 s45, 13
	s_cbranch_scc0 .LBB0_82
	v_lshl_or_b32 v132, s16, 7, v160
	v_lshl_add_u32 v162, s20, 8, v3
	v_ashrrev_i32_e32 v133, 31, v132
	v_mov_b64_e32 v[156:157], s[6:7]
	s_movk_i32 s9, 0x1600
	v_mad_i64_i32 v[134:135], s[16:17], v162, s9, v[156:157]
	v_lshlrev_b64 v[158:159], 1, v[132:133]
	v_lshl_add_u64 v[132:133], v[134:135], 0, v[158:159]
	v_mul_f32_e32 v134, 0xbfb8aa3b, v128
	v_exp_f32_e32 v134, v134
	s_and_b64 vcc, exec, s[4:5]
	s_mov_b32 s20, s12
	s_mov_b64 s[24:25], s[18:19]
	v_add_f32_e32 v134, 1.0, v134
	v_rcp_f32_e32 v134, v134
	s_mov_b64 s[26:27], s[14:15]
	v_mul_f32_e32 v128, v128, v134
	v_mul_f32_e32 v124, v128, v124
	v_mul_f32_e32 v128, 0xbfb8aa3b, v129
	v_exp_f32_e32 v128, v128
	s_nop 0
	v_add_f32_e32 v128, 1.0, v128
	v_rcp_f32_e32 v128, v128
	s_nop 0
	v_mul_f32_e32 v128, v129, v128
	v_mul_f32_e32 v125, v128, v125
	v_cvt_pk_bf16_f32 v124, v124, v125
	v_mul_f32_e32 v125, 0xbfb8aa3b, v130
	v_exp_f32_e32 v125, v125
	s_nop 0
	v_add_f32_e32 v125, 1.0, v125
	v_rcp_f32_e32 v125, v125
	s_nop 0
	v_mul_f32_e32 v125, v130, v125
	v_mul_f32_e32 v125, v125, v126
	v_mul_f32_e32 v126, 0xbfb8aa3b, v131
	v_exp_f32_e32 v126, v126
	s_nop 0
	v_add_f32_e32 v126, 1.0, v126
	v_rcp_f32_e32 v126, v126
	s_nop 0
	v_mul_f32_e32 v126, v131, v126
	v_mul_f32_e32 v126, v126, v127
	v_cvt_pk_bf16_f32 v125, v125, v126
	v_mul_f32_e32 v126, 0xbfb8aa3b, v120
	v_exp_f32_e32 v126, v126
	s_nop 0
	v_add_f32_e32 v126, 1.0, v126
	v_rcp_f32_e32 v126, v126
	s_nop 0
	v_mul_f32_e32 v120, v120, v126
	v_mul_f32_e32 v116, v120, v116
	v_mul_f32_e32 v120, 0xbfb8aa3b, v121
	v_exp_f32_e32 v120, v120
	s_nop 0
	v_add_f32_e32 v120, 1.0, v120
	v_rcp_f32_e32 v120, v120
	s_nop 0
	v_mul_f32_e32 v120, v121, v120
	v_mul_f32_e32 v117, v120, v117
	v_cvt_pk_bf16_f32 v126, v116, v117
	v_mul_f32_e32 v116, 0xbfb8aa3b, v122
	v_exp_f32_e32 v116, v116
	v_mul_f32_e32 v117, 0xbfb8aa3b, v123
	v_exp_f32_e32 v117, v117
	v_add_f32_e32 v116, 1.0, v116
	v_rcp_f32_e32 v116, v116
	v_add_f32_e32 v117, 1.0, v117
	v_rcp_f32_e32 v117, v117
	v_mul_f32_e32 v116, v122, v116
	v_mul_f32_e32 v116, v116, v118
	v_mul_f32_e32 v118, 0xbfb8aa3b, v112
	v_exp_f32_e32 v118, v118
	v_mul_f32_e32 v117, v123, v117
	v_mul_f32_e32 v117, v117, v119
	v_cvt_pk_bf16_f32 v127, v116, v117
	v_add_f32_e32 v118, 1.0, v118
	v_rcp_f32_e32 v118, v118
	v_or_b32_e32 v116, 16, v162
	v_mad_i64_i32 v[116:117], s[16:17], v116, s9, v[156:157]
	v_mul_f32_e32 v112, v112, v118
	v_mul_f32_e32 v108, v112, v108
	v_mul_f32_e32 v112, 0xbfb8aa3b, v113
	v_exp_f32_e32 v112, v112
	v_lshl_add_u64 v[116:117], v[116:117], 0, v[158:159]
	global_store_dwordx4 v[132:133], v[124:127], off
	v_add_f32_e32 v112, 1.0, v112
	v_rcp_f32_e32 v112, v112
	s_nop 0
	v_mul_f32_e32 v112, v113, v112
	v_mul_f32_e32 v109, v112, v109
	v_cvt_pk_bf16_f32 v108, v108, v109
	v_mul_f32_e32 v109, 0xbfb8aa3b, v114
	v_exp_f32_e32 v109, v109
	s_nop 0
	v_add_f32_e32 v109, 1.0, v109
	v_rcp_f32_e32 v109, v109
	s_nop 0
	v_mul_f32_e32 v109, v114, v109
	v_mul_f32_e32 v109, v109, v110
	v_mul_f32_e32 v110, 0xbfb8aa3b, v115
	v_exp_f32_e32 v110, v110
	s_nop 0
	v_add_f32_e32 v110, 1.0, v110
	v_rcp_f32_e32 v110, v110
	s_nop 0
	v_mul_f32_e32 v110, v115, v110
	v_mul_f32_e32 v110, v110, v111
	v_cvt_pk_bf16_f32 v109, v109, v110
	v_mul_f32_e32 v110, 0xbfb8aa3b, v104
	v_exp_f32_e32 v110, v110
	s_nop 0
	v_add_f32_e32 v110, 1.0, v110
	v_rcp_f32_e32 v110, v110
	s_nop 0
	v_mul_f32_e32 v104, v104, v110
	v_mul_f32_e32 v100, v104, v100
	v_mul_f32_e32 v104, 0xbfb8aa3b, v105
	v_exp_f32_e32 v104, v104
	s_nop 0
	v_add_f32_e32 v104, 1.0, v104
	v_rcp_f32_e32 v104, v104
	s_nop 0
	v_mul_f32_e32 v104, v105, v104
	v_mul_f32_e32 v101, v104, v101
	v_cvt_pk_bf16_f32 v110, v100, v101
	v_mul_f32_e32 v100, 0xbfb8aa3b, v106
	v_exp_f32_e32 v100, v100
	v_mul_f32_e32 v101, 0xbfb8aa3b, v107
	v_exp_f32_e32 v101, v101
	v_add_f32_e32 v100, 1.0, v100
	v_rcp_f32_e32 v100, v100
	v_add_f32_e32 v101, 1.0, v101
	v_rcp_f32_e32 v101, v101
	v_mul_f32_e32 v100, v106, v100
	v_mul_f32_e32 v100, v100, v102
	v_mul_f32_e32 v102, 0xbfb8aa3b, v96
	v_exp_f32_e32 v102, v102
	v_mul_f32_e32 v101, v107, v101
	v_mul_f32_e32 v101, v101, v103
	v_cvt_pk_bf16_f32 v111, v100, v101
	v_add_f32_e32 v102, 1.0, v102
	v_rcp_f32_e32 v102, v102
	v_or_b32_e32 v100, 32, v162
	v_mad_i64_i32 v[100:101], s[16:17], v100, s9, v[156:157]
	v_mul_f32_e32 v96, v96, v102
	v_mul_f32_e32 v92, v96, v92
	v_mul_f32_e32 v96, 0xbfb8aa3b, v97
	v_exp_f32_e32 v96, v96
	v_lshl_add_u64 v[100:101], v[100:101], 0, v[158:159]
	global_store_dwordx4 v[116:117], v[108:111], off
	v_add_f32_e32 v96, 1.0, v96
	v_rcp_f32_e32 v96, v96
	s_nop 0
	v_mul_f32_e32 v96, v97, v96
	v_mul_f32_e32 v93, v96, v93
	v_cvt_pk_bf16_f32 v92, v92, v93
	v_mul_f32_e32 v93, 0xbfb8aa3b, v98
	v_exp_f32_e32 v93, v93
	s_nop 0
	v_add_f32_e32 v93, 1.0, v93
	v_rcp_f32_e32 v93, v93
	s_nop 0
	v_mul_f32_e32 v93, v98, v93
	v_mul_f32_e32 v93, v93, v94
	v_mul_f32_e32 v94, 0xbfb8aa3b, v99
	v_exp_f32_e32 v94, v94
	s_nop 0
	v_add_f32_e32 v94, 1.0, v94
	v_rcp_f32_e32 v94, v94
	s_nop 0
	v_mul_f32_e32 v94, v99, v94
	v_mul_f32_e32 v94, v94, v95
	v_cvt_pk_bf16_f32 v93, v93, v94
	v_mul_f32_e32 v94, 0xbfb8aa3b, v88
	v_exp_f32_e32 v94, v94
	s_nop 0
	v_add_f32_e32 v94, 1.0, v94
	v_rcp_f32_e32 v94, v94
	s_nop 0
	v_mul_f32_e32 v88, v88, v94
	v_mul_f32_e32 v84, v88, v84
	v_mul_f32_e32 v88, 0xbfb8aa3b, v89
	v_exp_f32_e32 v88, v88
	s_nop 0
	v_add_f32_e32 v88, 1.0, v88
	v_rcp_f32_e32 v88, v88
	s_nop 0
	v_mul_f32_e32 v88, v89, v88
	v_mul_f32_e32 v85, v88, v85
	v_cvt_pk_bf16_f32 v94, v84, v85
	v_mul_f32_e32 v84, 0xbfb8aa3b, v90
; __device__ __forceinline__ unsigned pk2(float lo, float hi) { unsigned r; asm("v_cvt_pk_bf16_f32 %0, %1, %2" : "=v"(r) : "v"(lo), "v"(hi)); return r; }
; __device__ __forceinline__ float silu(float x) { return x * sigm(x); }
;     __device__ __forceinline__ void operator()(const f32x4 (&acc)[2][2][4][2], const Unit& u, int wr, int wc, int fr, int fq) const {
;         const int row0 = u.pm * BM + wr * 64 + fr, col0 = u.pn * HALF + wc * 32 + 8 * fq;
; #pragma unroll
;         for (int ai = 0; ai < 2; ++ai)
; #pragma unroll
;             for (int m = 0; m < 4; ++m) { bf16_t* rowp = O + (size_t)(row0 + ai * HALF + m * 16) * ldc + col0;
;                 const f32x4 g0 = acc[ai][0][m][0], g1 = acc[ai][0][m][1], u0 = acc[ai][1][m][0], u1 = acc[ai][1][m][1];
;                 u32x4 w; w.x = pk2(silu(g0[0]) * u0[0], silu(g0[1]) * u0[1]); w.y = pk2(silu(g0[2]) * u0[2], silu(g0[3]) * u0[3]);
;                 w.z = pk2(silu(g1[0]) * u1[0], silu(g1[1]) * u1[1]); w.w = pk2(silu(g1[2]) * u1[2], silu(g1[3]) * u1[3]);
;                 *(u32x4*)rowp = w; }
	v_exp_f32_e32 v84, v84
	v_mul_f32_e32 v85, 0xbfb8aa3b, v91
	v_exp_f32_e32 v85, v85
	v_add_f32_e32 v84, 1.0, v84
	v_rcp_f32_e32 v84, v84
	v_add_f32_e32 v85, 1.0, v85
	v_rcp_f32_e32 v85, v85
	v_mul_f32_e32 v84, v90, v84
	v_mul_f32_e32 v84, v84, v86
	v_mul_f32_e32 v86, 0xbfb8aa3b, v80
	v_exp_f32_e32 v86, v86
	v_mul_f32_e32 v85, v91, v85
	v_mul_f32_e32 v85, v85, v87
	v_cvt_pk_bf16_f32 v95, v84, v85
	v_add_f32_e32 v86, 1.0, v86
	v_rcp_f32_e32 v86, v86
	v_or_b32_e32 v84, 48, v162
	v_mad_i64_i32 v[84:85], s[16:17], v84, s9, v[156:157]
	v_mul_f32_e32 v80, v80, v86
	v_mul_f32_e32 v76, v80, v76
	v_mul_f32_e32 v80, 0xbfb8aa3b, v81
	v_exp_f32_e32 v80, v80
	v_lshl_add_u64 v[84:85], v[84:85], 0, v[158:159]
	global_store_dwordx4 v[100:101], v[92:95], off
	v_add_f32_e32 v80, 1.0, v80
	v_rcp_f32_e32 v80, v80
	s_nop 0
	v_mul_f32_e32 v80, v81, v80
	v_mul_f32_e32 v77, v80, v77
	v_cvt_pk_bf16_f32 v76, v76, v77
	v_mul_f32_e32 v77, 0xbfb8aa3b, v82
	v_exp_f32_e32 v77, v77
	s_nop 0
	v_add_f32_e32 v77, 1.0, v77
	v_rcp_f32_e32 v77, v77
	s_nop 0
	v_mul_f32_e32 v77, v82, v77
	v_mul_f32_e32 v77, v77, v78
	v_mul_f32_e32 v78, 0xbfb8aa3b, v83
	v_exp_f32_e32 v78, v78
	s_nop 0
	v_add_f32_e32 v78, 1.0, v78
	v_rcp_f32_e32 v78, v78
	s_nop 0
	v_mul_f32_e32 v78, v83, v78
	v_mul_f32_e32 v78, v78, v79
	v_cvt_pk_bf16_f32 v77, v77, v78
	v_mul_f32_e32 v78, 0xbfb8aa3b, v72
	v_exp_f32_e32 v78, v78
	s_nop 0
	v_add_f32_e32 v78, 1.0, v78
	v_rcp_f32_e32 v78, v78
	s_nop 0
	v_mul_f32_e32 v72, v72, v78
	v_mul_f32_e32 v68, v72, v68
	v_mul_f32_e32 v72, 0xbfb8aa3b, v73
	v_exp_f32_e32 v72, v72
	s_nop 0
	v_add_f32_e32 v72, 1.0, v72
	v_rcp_f32_e32 v72, v72
	s_nop 0
	v_mul_f32_e32 v72, v73, v72
	v_mul_f32_e32 v69, v72, v69
	v_cvt_pk_bf16_f32 v78, v68, v69
	v_mul_f32_e32 v68, 0xbfb8aa3b, v74
	v_exp_f32_e32 v68, v68
	v_mul_f32_e32 v69, 0xbfb8aa3b, v75
	v_exp_f32_e32 v69, v69
	v_add_f32_e32 v68, 1.0, v68
	v_rcp_f32_e32 v68, v68
	v_add_f32_e32 v69, 1.0, v69
	v_rcp_f32_e32 v69, v69
	v_mul_f32_e32 v68, v74, v68
	v_mul_f32_e32 v68, v68, v70
	v_mul_f32_e32 v70, 0xbfb8aa3b, v64
	v_exp_f32_e32 v70, v70
	v_mul_f32_e32 v69, v75, v69
	v_mul_f32_e32 v69, v69, v71
	v_cvt_pk_bf16_f32 v79, v68, v69
	v_add_f32_e32 v70, 1.0, v70
	v_rcp_f32_e32 v70, v70
	v_add_u32_e32 v68, 0x80, v162
	v_mad_i64_i32 v[68:69], s[16:17], v68, s9, v[156:157]
	v_mul_f32_e32 v64, v64, v70
	v_mul_f32_e32 v60, v64, v60
	v_mul_f32_e32 v64, 0xbfb8aa3b, v65
	v_exp_f32_e32 v64, v64
	v_lshl_add_u64 v[68:69], v[68:69], 0, v[158:159]
	global_store_dwordx4 v[84:85], v[76:79], off
	v_add_f32_e32 v64, 1.0, v64
	v_rcp_f32_e32 v64, v64
	s_nop 0
	v_mul_f32_e32 v64, v65, v64
	v_mul_f32_e32 v61, v64, v61
	v_cvt_pk_bf16_f32 v60, v60, v61
	v_mul_f32_e32 v61, 0xbfb8aa3b, v66
	v_exp_f32_e32 v61, v61
	s_nop 0
	v_add_f32_e32 v61, 1.0, v61
	v_rcp_f32_e32 v61, v61
	s_nop 0
	v_mul_f32_e32 v61, v66, v61
	v_mul_f32_e32 v61, v61, v62
	v_mul_f32_e32 v62, 0xbfb8aa3b, v67
	v_exp_f32_e32 v62, v62
	s_nop 0
	v_add_f32_e32 v62, 1.0, v62
	v_rcp_f32_e32 v62, v62
	s_nop 0
	v_mul_f32_e32 v62, v67, v62
	v_mul_f32_e32 v62, v62, v63
	v_cvt_pk_bf16_f32 v61, v61, v62
	v_mul_f32_e32 v62, 0xbfb8aa3b, v56
	v_exp_f32_e32 v62, v62
	s_nop 0
	v_add_f32_e32 v62, 1.0, v62
	v_rcp_f32_e32 v62, v62
	s_nop 0
	v_mul_f32_e32 v56, v56, v62
	v_mul_f32_e32 v52, v56, v52
	v_mul_f32_e32 v56, 0xbfb8aa3b, v57
	v_exp_f32_e32 v56, v56
	s_nop 0
	v_add_f32_e32 v56, 1.0, v56
	v_rcp_f32_e32 v56, v56
	s_nop 0
	v_mul_f32_e32 v56, v57, v56
	v_mul_f32_e32 v53, v56, v53
	v_cvt_pk_bf16_f32 v62, v52, v53
	v_mul_f32_e32 v52, 0xbfb8aa3b, v58
	v_exp_f32_e32 v52, v52
	v_mul_f32_e32 v53, 0xbfb8aa3b, v59
	v_exp_f32_e32 v53, v53
	v_add_f32_e32 v52, 1.0, v52
	v_rcp_f32_e32 v52, v52
	v_add_f32_e32 v53, 1.0, v53
	v_rcp_f32_e32 v53, v53
	v_mul_f32_e32 v52, v58, v52
	v_mul_f32_e32 v52, v52, v54
	v_mul_f32_e32 v54, 0xbfb8aa3b, v48
	v_exp_f32_e32 v54, v54
	v_mul_f32_e32 v53, v59, v53
	v_mul_f32_e32 v53, v53, v55
	v_cvt_pk_bf16_f32 v63, v52, v53
	v_add_f32_e32 v54, 1.0, v54
	v_rcp_f32_e32 v54, v54
	v_add_u32_e32 v52, 0x90, v162
	v_mad_i64_i32 v[52:53], s[16:17], v52, s9, v[156:157]
	v_mul_f32_e32 v48, v48, v54
	v_mul_f32_e32 v44, v48, v44
	v_mul_f32_e32 v48, 0xbfb8aa3b, v49
	v_exp_f32_e32 v48, v48
	v_lshl_add_u64 v[52:53], v[52:53], 0, v[158:159]
	global_store_dwordx4 v[68:69], v[60:63], off
	v_add_f32_e32 v48, 1.0, v48
	v_rcp_f32_e32 v48, v48
	s_nop 0
	v_mul_f32_e32 v48, v49, v48
	v_mul_f32_e32 v45, v48, v45
	v_cvt_pk_bf16_f32 v44, v44, v45
	v_mul_f32_e32 v45, 0xbfb8aa3b, v50
	v_exp_f32_e32 v45, v45
	s_nop 0
	v_add_f32_e32 v45, 1.0, v45
	v_rcp_f32_e32 v45, v45
	s_nop 0
	v_mul_f32_e32 v45, v50, v45
	v_mul_f32_e32 v45, v45, v46
	v_mul_f32_e32 v46, 0xbfb8aa3b, v51
; __device__ __forceinline__ unsigned pk2(float lo, float hi) { unsigned r; asm("v_cvt_pk_bf16_f32 %0, %1, %2" : "=v"(r) : "v"(lo), "v"(hi)); return r; }
; __device__ __forceinline__ float silu(float x) { return x * sigm(x); }
; #define PG8_WAIT_V(n) asm volatile("s_waitcnt vmcnt(" #n ")" ::: "memory")
; #define PG8_BAR __builtin_amdgcn_s_barrier()
;     __device__ __forceinline__ void operator()(const f32x4 (&acc)[2][2][4][2], const Unit& u, int wr, int wc, int fr, int fq) const {
;         const int row0 = u.pm * BM + wr * 64 + fr, col0 = u.pn * HALF + wc * 32 + 8 * fq;
; #pragma unroll
;         for (int ai = 0; ai < 2; ++ai)
; #pragma unroll
;             for (int m = 0; m < 4; ++m) { bf16_t* rowp = O + (size_t)(row0 + ai * HALF + m * 16) * ldc + col0;
;                 const f32x4 g0 = acc[ai][0][m][0], g1 = acc[ai][0][m][1], u0 = acc[ai][1][m][0], u1 = acc[ai][1][m][1];
;                 u32x4 w; w.x = pk2(silu(g0[0]) * u0[0], silu(g0[1]) * u0[1]); w.y = pk2(silu(g0[2]) * u0[2], silu(g0[3]) * u0[3]);
;                 w.z = pk2(silu(g1[0]) * u1[0], silu(g1[1]) * u1[1]); w.w = pk2(silu(g1[2]) * u1[2], silu(g1[3]) * u1[3]);
;                 *(u32x4*)rowp = w; }
; template <class Epi>
; __device__ __forceinline__ void gemm_phase(LAS unsigned char* lds, const Gemm g, const int G, const int cidx, const Epi& E) {
;     ...
;     PG8_WAIT_V(0);
;     if (wr == 0) PG8_BAR;
;     PG8_BAR;
	v_exp_f32_e32 v46, v46
	s_nop 0
	v_add_f32_e32 v46, 1.0, v46
	v_rcp_f32_e32 v46, v46
	s_nop 0
	v_mul_f32_e32 v46, v51, v46
	v_mul_f32_e32 v46, v46, v47
	v_cvt_pk_bf16_f32 v45, v45, v46
	v_mul_f32_e32 v46, 0xbfb8aa3b, v40
	v_exp_f32_e32 v46, v46
	s_nop 0
	v_add_f32_e32 v46, 1.0, v46
	v_rcp_f32_e32 v46, v46
	s_nop 0
	v_mul_f32_e32 v40, v40, v46
	v_mul_f32_e32 v36, v40, v36
	v_mul_f32_e32 v40, 0xbfb8aa3b, v41
	v_exp_f32_e32 v40, v40
	s_nop 0
	v_add_f32_e32 v40, 1.0, v40
	v_rcp_f32_e32 v40, v40
	s_nop 0
	v_mul_f32_e32 v40, v41, v40
	v_mul_f32_e32 v37, v40, v37
	v_cvt_pk_bf16_f32 v46, v36, v37
	v_mul_f32_e32 v36, 0xbfb8aa3b, v42
	v_exp_f32_e32 v36, v36
	v_mul_f32_e32 v37, 0xbfb8aa3b, v43
	v_exp_f32_e32 v37, v37
	v_add_f32_e32 v36, 1.0, v36
	v_rcp_f32_e32 v36, v36
	v_add_f32_e32 v37, 1.0, v37
	v_rcp_f32_e32 v37, v37
	v_mul_f32_e32 v36, v42, v36
	v_mul_f32_e32 v36, v36, v38
	v_mul_f32_e32 v38, 0xbfb8aa3b, v32
	v_exp_f32_e32 v38, v38
	v_mul_f32_e32 v37, v43, v37
	v_mul_f32_e32 v37, v37, v39
	v_cvt_pk_bf16_f32 v47, v36, v37
	v_add_f32_e32 v38, 1.0, v38
	v_rcp_f32_e32 v38, v38
	v_add_u32_e32 v36, 0xa0, v162
	v_mad_i64_i32 v[36:37], s[16:17], v36, s9, v[156:157]
	v_mul_f32_e32 v32, v32, v38
	v_mul_f32_e32 v28, v32, v28
	v_mul_f32_e32 v32, 0xbfb8aa3b, v33
	v_exp_f32_e32 v32, v32
	v_lshl_add_u64 v[36:37], v[36:37], 0, v[158:159]
	global_store_dwordx4 v[52:53], v[44:47], off
	v_add_f32_e32 v32, 1.0, v32
	v_rcp_f32_e32 v32, v32
	s_nop 0
	v_mul_f32_e32 v32, v33, v32
	v_mul_f32_e32 v29, v32, v29
	v_cvt_pk_bf16_f32 v28, v28, v29
	v_mul_f32_e32 v29, 0xbfb8aa3b, v34
	v_exp_f32_e32 v29, v29
	s_nop 0
	v_add_f32_e32 v29, 1.0, v29
	v_rcp_f32_e32 v29, v29
	s_nop 0
	v_mul_f32_e32 v29, v34, v29
	v_mul_f32_e32 v29, v29, v30
	v_mul_f32_e32 v30, 0xbfb8aa3b, v35
	v_exp_f32_e32 v30, v30
	s_nop 0
	v_add_f32_e32 v30, 1.0, v30
	v_rcp_f32_e32 v30, v30
	s_nop 0
	v_mul_f32_e32 v30, v35, v30
	v_mul_f32_e32 v30, v30, v31
	v_cvt_pk_bf16_f32 v29, v29, v30
	v_mul_f32_e32 v30, 0xbfb8aa3b, v24
	v_exp_f32_e32 v30, v30
	s_nop 0
	v_add_f32_e32 v30, 1.0, v30
	v_rcp_f32_e32 v30, v30
	s_nop 0
	v_mul_f32_e32 v24, v24, v30
	v_mul_f32_e32 v20, v24, v20
	v_mul_f32_e32 v24, 0xbfb8aa3b, v25
	v_exp_f32_e32 v24, v24
	s_nop 0
	v_add_f32_e32 v24, 1.0, v24
	v_rcp_f32_e32 v24, v24
	s_nop 0
	v_mul_f32_e32 v24, v25, v24
	v_mul_f32_e32 v21, v24, v21
	v_cvt_pk_bf16_f32 v30, v20, v21
	v_mul_f32_e32 v20, 0xbfb8aa3b, v26
	v_exp_f32_e32 v20, v20
	v_mul_f32_e32 v21, 0xbfb8aa3b, v27
	v_exp_f32_e32 v21, v21
	v_add_f32_e32 v20, 1.0, v20
	v_rcp_f32_e32 v20, v20
	v_add_f32_e32 v21, 1.0, v21
	v_rcp_f32_e32 v21, v21
	v_mul_f32_e32 v20, v26, v20
	v_mul_f32_e32 v20, v20, v22
	v_mul_f32_e32 v22, 0xbfb8aa3b, v16
	v_exp_f32_e32 v22, v22
	v_mul_f32_e32 v21, v27, v21
	v_mul_f32_e32 v21, v21, v23
	v_cvt_pk_bf16_f32 v31, v20, v21
	v_add_f32_e32 v22, 1.0, v22
	v_rcp_f32_e32 v22, v22
	v_add_u32_e32 v20, 0xb0, v162
	v_mad_i64_i32 v[20:21], s[16:17], v20, s9, v[156:157]
	v_mul_f32_e32 v16, v16, v22
	v_mul_f32_e32 v12, v16, v12
	v_mul_f32_e32 v16, 0xbfb8aa3b, v17
	v_exp_f32_e32 v16, v16
	v_lshl_add_u64 v[20:21], v[20:21], 0, v[158:159]
	s_mov_b32 s16, s8
	global_store_dwordx4 v[36:37], v[28:31], off
	v_add_f32_e32 v16, 1.0, v16
	v_rcp_f32_e32 v16, v16
	s_nop 0
	v_mul_f32_e32 v16, v17, v16
	v_mul_f32_e32 v13, v16, v13
	v_cvt_pk_bf16_f32 v12, v12, v13
	v_mul_f32_e32 v13, 0xbfb8aa3b, v18
	v_exp_f32_e32 v13, v13
	s_nop 0
	v_add_f32_e32 v13, 1.0, v13
	v_rcp_f32_e32 v13, v13
	s_nop 0
	v_mul_f32_e32 v13, v18, v13
	v_mul_f32_e32 v13, v13, v14
	v_mul_f32_e32 v14, 0xbfb8aa3b, v19
	v_exp_f32_e32 v14, v14
	s_nop 0
	v_add_f32_e32 v14, 1.0, v14
	v_rcp_f32_e32 v14, v14
	s_nop 0
	v_mul_f32_e32 v14, v19, v14
	v_mul_f32_e32 v14, v14, v15
	v_cvt_pk_bf16_f32 v13, v13, v14
	v_mul_f32_e32 v14, 0xbfb8aa3b, v8
	v_exp_f32_e32 v14, v14
	s_nop 0
	v_add_f32_e32 v14, 1.0, v14
	v_rcp_f32_e32 v14, v14
	s_nop 0
	v_mul_f32_e32 v8, v8, v14
	v_mul_f32_e32 v4, v8, v4
	v_mul_f32_e32 v8, 0xbfb8aa3b, v9
	v_exp_f32_e32 v8, v8
	s_nop 0
	v_add_f32_e32 v8, 1.0, v8
	v_rcp_f32_e32 v8, v8
	s_nop 0
	v_mul_f32_e32 v8, v9, v8
	v_mul_f32_e32 v5, v8, v5
	v_cvt_pk_bf16_f32 v14, v4, v5
	v_mul_f32_e32 v4, 0xbfb8aa3b, v10
	v_mul_f32_e32 v5, 0xbfb8aa3b, v11
	v_exp_f32_e32 v4, v4
	v_exp_f32_e32 v5, v5
	v_add_f32_e32 v4, 1.0, v4
	v_add_f32_e32 v5, 1.0, v5
	v_rcp_f32_e32 v4, v4
	v_rcp_f32_e32 v5, v5
	v_mul_f32_e32 v4, v10, v4
	v_mul_f32_e32 v5, v11, v5
	v_mul_f32_e32 v4, v4, v6
	v_mul_f32_e32 v5, v5, v7
	v_cvt_pk_bf16_f32 v15, v4, v5
	global_store_dwordx4 v[20:21], v[12:15], off
	s_cbranch_vccz .LBB0_79
	s_waitcnt vmcnt(0)
	s_cmpk_gt_u32 s95, 0xff
	s_mov_b32 s73, s83
	v_readlane_b32 s79, v255, 21
	s_cbranch_scc1 .LBB0_86
	s_barrier

; #define PG8_STAGE(bufoff, gbase, voff) do { _Pragma("unroll") for (int _i = 0; _i < 2; ++_i) \
;         __builtin_amdgcn_global_load_lds((const unsigned*)((const char*)(gbase) + (voff)[_i]), (LAS unsigned*)(lds + (bufoff) + ldsw + _i * 8192), 16, 0, 0); } while (0)
; #define PG8_LDA(dst, b, h) do { _Pragma("unroll") for (int m = 0; m < 4; ++m) _Pragma("unroll") for (int k = 0; k < 2; ++k) dst[m][k] = *(const LAS bf16x8*)(lds + PG8_SA(b, h) + aoff + m * 2048 + k * 1024); } while (0)
; #define PG8_LDB(dst, b, h) do { _Pragma("unroll") for (int n = 0; n < 2; ++n) _Pragma("unroll") for (int k = 0; k < 2; ++k) dst[n][k] = *(const LAS bf16x8*)(lds + PG8_SB(b, h) + boff + n * 2048 + k * 1024); } while (0)
; #define PG8_MMA(ai, bj, At, Bt) do { __builtin_amdgcn_s_setprio(1); _Pragma("unroll") for (int m = 0; m < 4; ++m) _Pragma("unroll") for (int n = 0; n < 2; ++n) _Pragma("unroll") for (int k = 0; k < 2; ++k) \
;         acc[ai][bj][m][n] = __builtin_amdgcn_mfma_f32_16x16x32_bf16(Bt[n][k], At[m][k], acc[ai][bj][m][n], 0, 0, 0); __builtin_amdgcn_s_setprio(0); } while (0)
; #define PG8_WAIT_V(n) asm volatile("s_waitcnt vmcnt(" #n ")" ::: "memory")
; #define PG8_WAIT_L(n) asm volatile("s_waitcnt lgkmcnt(" #n ")" ::: "memory")
; template <class Epi>
; __device__ __forceinline__ void gemm_phase(LAS unsigned char* lds, const Gemm g, const int G, const int cidx, const Epi& E) {
;     ...
;         const char* nA = has_next ? PG8_ABASE(nxt) : cA; const char* nB = has_next ? (const char*)g.Bt + (size_t)nxt.pn * tstep : cB;
;         for (int t = 0; t < nt; t += 2) {
;             const bool last = (t == nt - 2);
;             const char* a1 = cA + (size_t)(t + 1) * kstep;
;             const char* a2 = last ? nA : cA + (size_t)(t + 2) * kstep; const char* b2 = last ? nB : cB + (size_t)(t + 2) * kstep;
;             const char* a3 = a2 + kstep; const char* b3 = b2 + kstep;
;             PG8_LDB(B0, 0, 0); PG8_LDB(B1, 0, 1); PG8_SCHED; PG8_LDA(At, 0, 0); PG8_STAGE(PG8_SA(1, 1), a1 + hstep, voffA);
;             PG8_WAIT_V(8); PG8_WAIT_L(0); PG8_BAR; PG8_MMA(0, 0, At, B0); PG8_MMA(0, 1, At, B1); PG8_BAR; PG8_SCHED;
;             PG8_LDA(At, 0, 1); PG8_STAGE(PG8_SB(0, 0), b2, voffB); PG8_STAGE(PG8_SB(0, 1), b2 + hstep, voffB); PG8_STAGE(PG8_SA(0, 0), a2, voffA);
;             PG8_WAIT_V(8); PG8_WAIT_L(0); PG8_BAR; PG8_MMA(1, 0, At, B0); PG8_MMA(1, 1, At, B1); PG8_BAR; PG8_SCHED;
.LBB0_600:
	s_ashr_i32 s11, s10, 31
	v_cmp_lt_i64_e32 vcc, s[12:13], v[244:245]
	s_lshl_b64 s[12:13], s[10:11], 19
	s_add_u32 s12, s74, s12
	s_addc_u32 s13, s75, s13
	s_and_b64 s[14:15], vcc, exec
	s_cselect_b32 s11, s13, s25
	s_cselect_b32 s19, s12, s24
	s_ashr_i32 s9, s8, 31
	s_lshl_b64 s[14:15], s[8:9], 19
	s_add_u32 s14, s88, s14
	s_addc_u32 s15, s94, s15
	s_and_b64 s[26:27], vcc, exec
	s_cselect_b32 s9, s15, s21
	s_cselect_b32 s33, s14, s20
	s_add_u32 s42, s20, 0x100
	s_addc_u32 s44, s21, 0
	s_add_u32 s20, s24, 0x40080
	s_addc_u32 s21, s25, 0
	s_mov_b32 s45, -2
	s_add_u32 s24, s20, 0xfffc0080
	s_addc_u32 s25, s21, -1
	s_add_i32 s43, 0, 0x10000
	s_cmp_eq_u32 s45, 12
	s_cselect_b32 s27, s11, s25
	s_cselect_b32 s26, s19, s24
	v_add_u32_e32 v132, s43, v145
	s_cselect_b32 s25, s9, s44
	s_cselect_b32 s24, s33, s42
	s_add_i32 s68, 0, 0x14000
	ds_read_b128 v[158:161], v132
	ds_read_b128 v[164:167], v132 offset:1024
	ds_read_b128 v[168:171], v132 offset:2048
	ds_read_b128 v[172:175], v132 offset:3072
	v_add_u32_e32 v132, s68, v145
	ds_read_b128 v[176:179], v132
	ds_read_b128 v[180:183], v132 offset:1024
	ds_read_b128 v[184:187], v132 offset:2048
	ds_read_b128 v[188:191], v132 offset:3072
	s_add_i32 m0, s97, 0xc000
	ds_read_b128 v[192:195], v163
	ds_read_b128 v[196:199], v163 offset:1024
	ds_read_b128 v[214:217], v163 offset:2048
	ds_read_b128 v[218:221], v163 offset:3072
	ds_read_b128 v[222:225], v163 offset:4096
	ds_read_b128 v[226:229], v163 offset:5120
	ds_read_b128 v[230:233], v163 offset:6144
	ds_read_b128 v[234:237], v163 offset:7168
	global_load_lds_dwordx4 v156, s[20:21]
	s_add_i32 m0, s97, 0xe000
	s_nop 0
	global_load_lds_dwordx4 v154, s[20:21]
	s_waitcnt vmcnt(8)
	s_waitcnt lgkmcnt(0)
	s_barrier
	s_setprio 1
	s_waitcnt lgkmcnt(0)
	v_mfma_f32_16x16x32_bf16 v[128:131], v[158:161], v[192:195], 0
	v_mfma_f32_16x16x32_bf16 v[124:127], v[168:171], v[192:195], 0
	v_mfma_f32_16x16x32_bf16 v[120:123], v[158:161], v[214:217], 0
	v_mfma_f32_16x16x32_bf16 v[112:115], v[168:171], v[214:217], 0
	v_mfma_f32_16x16x32_bf16 v[104:107], v[158:161], v[222:225], 0
	v_mfma_f32_16x16x32_bf16 v[96:99], v[168:171], v[222:225], 0
	v_mfma_f32_16x16x32_bf16 v[88:91], v[158:161], v[230:233], 0
	v_mfma_f32_16x16x32_bf16 v[80:83], v[168:171], v[230:233], 0
	v_mfma_f32_16x16x32_bf16 v[128:131], v[164:167], v[196:199], v[128:131]
	v_mfma_f32_16x16x32_bf16 v[124:127], v[172:175], v[196:199], v[124:127]
	v_mfma_f32_16x16x32_bf16 v[120:123], v[164:167], v[218:221], v[120:123]
	v_mfma_f32_16x16x32_bf16 v[112:115], v[172:175], v[218:221], v[112:115]
	v_mfma_f32_16x16x32_bf16 v[104:107], v[164:167], v[226:229], v[104:107]
	v_mfma_f32_16x16x32_bf16 v[96:99], v[172:175], v[226:229], v[96:99]
	v_mfma_f32_16x16x32_bf16 v[88:91], v[164:167], v[234:237], v[88:91]
	v_mfma_f32_16x16x32_bf16 v[80:83], v[172:175], v[234:237], v[80:83]
	s_setprio 0
	s_setprio 1
	v_mfma_f32_16x16x32_bf16 v[116:119], v[176:179], v[192:195], 0
	v_mfma_f32_16x16x32_bf16 v[108:111], v[184:187], v[192:195], 0
	v_mfma_f32_16x16x32_bf16 v[100:103], v[176:179], v[214:217], 0
	v_mfma_f32_16x16x32_bf16 v[92:95], v[184:187], v[214:217], 0
	v_mfma_f32_16x16x32_bf16 v[84:87], v[176:179], v[222:225], 0
	v_mfma_f32_16x16x32_bf16 v[76:79], v[184:187], v[222:225], 0
	v_mfma_f32_16x16x32_bf16 v[72:75], v[176:179], v[230:233], 0
	v_mfma_f32_16x16x32_bf16 v[68:71], v[184:187], v[230:233], 0
	v_mfma_f32_16x16x32_bf16 v[116:119], v[180:183], v[196:199], v[116:119]
	v_mfma_f32_16x16x32_bf16 v[108:111], v[188:191], v[196:199], v[108:111]
	v_mfma_f32_16x16x32_bf16 v[100:103], v[180:183], v[218:221], v[100:103]
	v_mfma_f32_16x16x32_bf16 v[92:95], v[188:191], v[218:221], v[92:95]
	v_mfma_f32_16x16x32_bf16 v[84:87], v[180:183], v[226:229], v[84:87]
	v_mfma_f32_16x16x32_bf16 v[76:79], v[188:191], v[226:229], v[76:79]
	v_mfma_f32_16x16x32_bf16 v[72:75], v[180:183], v[234:237], v[72:75]
	v_mfma_f32_16x16x32_bf16 v[68:71], v[188:191], v[234:237], v[68:71]
	s_setprio 0
	s_barrier
	s_add_i32 s43, s43, s95
	s_mov_b32 m0, s43
	ds_read_b128 v[192:195], v163 offset:16384
	ds_read_b128 v[196:199], v163 offset:17408
	ds_read_b128 v[214:217], v163 offset:18432
	ds_read_b128 v[218:221], v163 offset:19456
	ds_read_b128 v[222:225], v163 offset:20480
	ds_read_b128 v[226:229], v163 offset:21504
	ds_read_b128 v[230:233], v163 offset:22528
	ds_read_b128 v[234:237], v163 offset:23552
	global_load_lds_dwordx4 v148, s[24:25]
	s_add_i32 m0, s43, 0x2000
	s_add_u32 s86, s24, 0x40000
	s_addc_u32 s87, s25, 0
	s_add_i32 s43, s68, s95
	global_load_lds_dwordx4 v0, s[24:25]
	s_mov_b32 m0, s43
	s_nop 0
	global_load_lds_dwordx4 v148, s[86:87]
	s_add_i32 m0, s43, 0x2000
	s_nop 0
	global_load_lds_dwordx4 v0, s[86:87]
	s_mov_b32 m0, s97
	s_nop 0
	global_load_lds_dwordx4 v150, s[26:27]
	s_mov_b32 m0, s22
	s_nop 0
	global_load_lds_dwordx4 v146, s[26:27]
	s_waitcnt vmcnt(8)
	s_waitcnt lgkmcnt(0)
	s_barrier
; #define PG8_STAGE(bufoff, gbase, voff) do { _Pragma("unroll") for (int _i = 0; _i < 2; ++_i) \
;         __builtin_amdgcn_global_load_lds((const unsigned*)((const char*)(gbase) + (voff)[_i]), (LAS unsigned*)(lds + (bufoff) + ldsw + _i * 8192), 16, 0, 0); } while (0)
; #define PG8_LDA(dst, b, h) do { _Pragma("unroll") for (int m = 0; m < 4; ++m) _Pragma("unroll") for (int k = 0; k < 2; ++k) dst[m][k] = *(const LAS bf16x8*)(lds + PG8_SA(b, h) + aoff + m * 2048 + k * 1024); } while (0)
; #define PG8_LDB(dst, b, h) do { _Pragma("unroll") for (int n = 0; n < 2; ++n) _Pragma("unroll") for (int k = 0; k < 2; ++k) dst[n][k] = *(const LAS bf16x8*)(lds + PG8_SB(b, h) + boff + n * 2048 + k * 1024); } while (0)
; #define PG8_MMA(ai, bj, At, Bt) do { __builtin_amdgcn_s_setprio(1); _Pragma("unroll") for (int m = 0; m < 4; ++m) _Pragma("unroll") for (int n = 0; n < 2; ++n) _Pragma("unroll") for (int k = 0; k < 2; ++k) \
;         acc[ai][bj][m][n] = __builtin_amdgcn_mfma_f32_16x16x32_bf16(Bt[n][k], At[m][k], acc[ai][bj][m][n], 0, 0, 0); __builtin_amdgcn_s_setprio(0); } while (0)
; #define PG8_WAIT_V(n) asm volatile("s_waitcnt vmcnt(" #n ")" ::: "memory")
; #define PG8_WAIT_L(n) asm volatile("s_waitcnt lgkmcnt(" #n ")" ::: "memory")
; #define PG8_BAR __builtin_amdgcn_s_barrier()
; #define PG8_SCHED __builtin_amdgcn_sched_barrier(0)
; template <class Epi>
; __device__ __forceinline__ void gemm_phase(LAS unsigned char* lds, const Gemm g, const int G, const int cidx, const Epi& E) {
;     ...
;             PG8_LDA(At, 0, 1); PG8_STAGE(PG8_SB(0, 0), b2, voffB); PG8_STAGE(PG8_SB(0, 1), b2 + hstep, voffB); PG8_STAGE(PG8_SA(0, 0), a2, voffA);
;             PG8_WAIT_V(8); PG8_WAIT_L(0); PG8_BAR; PG8_MMA(1, 0, At, B0); PG8_MMA(1, 1, At, B1); PG8_BAR; PG8_SCHED;
;             PG8_LDB(B0, 1, 0); PG8_LDB(B1, 1, 1); PG8_SCHED; PG8_LDA(At, 1, 0); PG8_STAGE(PG8_SA(0, 1), a2 + hstep, voffA);
;             PG8_WAIT_V(8); PG8_WAIT_L(0); PG8_BAR; PG8_MMA(0, 0, At, B0); PG8_MMA(0, 1, At, B1); PG8_BAR; PG8_SCHED;
;             PG8_LDA(At, 1, 1); PG8_STAGE(PG8_SB(1, 0), b3, voffB); PG8_STAGE(PG8_SB(1, 1), b3 + hstep, voffB); PG8_STAGE(PG8_SA(1, 0), a3, voffA);
;             PG8_WAIT_V(8); PG8_WAIT_L(0); PG8_BAR; PG8_MMA(1, 0, At, B0); PG8_MMA(1, 1, At, B1); PG8_BAR; PG8_SCHED;
	s_setprio 1
	s_waitcnt lgkmcnt(0)
	v_mfma_f32_16x16x32_bf16 v[64:67], v[158:161], v[192:195], 0
	v_mfma_f32_16x16x32_bf16 v[60:63], v[168:171], v[192:195], 0
	v_mfma_f32_16x16x32_bf16 v[56:59], v[158:161], v[214:217], 0
	v_mfma_f32_16x16x32_bf16 v[48:51], v[168:171], v[214:217], 0
	v_mfma_f32_16x16x32_bf16 v[40:43], v[158:161], v[222:225], 0
	v_mfma_f32_16x16x32_bf16 v[32:35], v[168:171], v[222:225], 0
	v_mfma_f32_16x16x32_bf16 v[24:27], v[158:161], v[230:233], 0
	v_mfma_f32_16x16x32_bf16 v[16:19], v[168:171], v[230:233], 0
	v_mfma_f32_16x16x32_bf16 v[64:67], v[164:167], v[196:199], v[64:67]
	v_mfma_f32_16x16x32_bf16 v[60:63], v[172:175], v[196:199], v[60:63]
	v_mfma_f32_16x16x32_bf16 v[56:59], v[164:167], v[218:221], v[56:59]
	v_mfma_f32_16x16x32_bf16 v[48:51], v[172:175], v[218:221], v[48:51]
	v_mfma_f32_16x16x32_bf16 v[40:43], v[164:167], v[226:229], v[40:43]
	v_mfma_f32_16x16x32_bf16 v[32:35], v[172:175], v[226:229], v[32:35]
	v_mfma_f32_16x16x32_bf16 v[24:27], v[164:167], v[234:237], v[24:27]
	v_mfma_f32_16x16x32_bf16 v[16:19], v[172:175], v[234:237], v[16:19]
	s_setprio 0
	s_setprio 1
	v_mfma_f32_16x16x32_bf16 v[52:55], v[176:179], v[192:195], 0
	v_mfma_f32_16x16x32_bf16 v[44:47], v[184:187], v[192:195], 0
	v_mfma_f32_16x16x32_bf16 v[36:39], v[176:179], v[214:217], 0
	v_mfma_f32_16x16x32_bf16 v[28:31], v[184:187], v[214:217], 0
	v_mfma_f32_16x16x32_bf16 v[20:23], v[176:179], v[222:225], 0
	v_mfma_f32_16x16x32_bf16 v[12:15], v[184:187], v[222:225], 0
	v_mfma_f32_16x16x32_bf16 v[8:11], v[176:179], v[230:233], 0
	v_mfma_f32_16x16x32_bf16 v[4:7], v[184:187], v[230:233], 0
	v_mfma_f32_16x16x32_bf16 v[52:55], v[180:183], v[196:199], v[52:55]
	v_mfma_f32_16x16x32_bf16 v[44:47], v[188:191], v[196:199], v[44:47]
	v_mfma_f32_16x16x32_bf16 v[36:39], v[180:183], v[218:221], v[36:39]
	v_mfma_f32_16x16x32_bf16 v[28:31], v[188:191], v[218:221], v[28:31]
	v_mfma_f32_16x16x32_bf16 v[20:23], v[180:183], v[226:229], v[20:23]
	v_mfma_f32_16x16x32_bf16 v[12:15], v[188:191], v[226:229], v[12:15]
	v_mfma_f32_16x16x32_bf16 v[8:11], v[180:183], v[234:237], v[8:11]
	v_mfma_f32_16x16x32_bf16 v[4:7], v[188:191], v[234:237], v[4:7]
	s_setprio 0
	s_barrier
	s_add_i32 s43, 0, 0x18000
	s_add_i32 s68, 0, 0x1c000
	v_add_u32_e32 v172, s43, v145
	v_add_u32_e32 v188, s68, v145
	ds_read_b128 v[158:161], v172
	ds_read_b128 v[164:167], v172 offset:1024
	ds_read_b128 v[168:171], v172 offset:2048
	ds_read_b128 v[172:175], v172 offset:3072
	ds_read_b128 v[176:179], v188
	ds_read_b128 v[180:183], v188 offset:1024
	ds_read_b128 v[184:187], v188 offset:2048
	ds_read_b128 v[188:191], v188 offset:3072
	s_add_u32 s98, s26, 0x80
	s_addc_u32 s99, s27, 0
	s_add_u32 s26, s26, 0x40000
	s_addc_u32 s27, s27, 0
	s_mov_b32 m0, s16
	ds_read_b128 v[192:195], v163 offset:32768
	ds_read_b128 v[196:199], v163 offset:33792
	ds_read_b128 v[214:217], v163 offset:34816
	ds_read_b128 v[218:221], v163 offset:35840
	ds_read_b128 v[222:225], v163 offset:36864
	ds_read_b128 v[226:229], v163 offset:37888
	ds_read_b128 v[230:233], v163 offset:38912
	ds_read_b128 v[234:237], v163 offset:39936
	global_load_lds_dwordx4 v150, s[26:27]
	s_mov_b32 m0, s17
	s_nop 0
	global_load_lds_dwordx4 v146, s[26:27]
	s_waitcnt vmcnt(8)
	s_waitcnt lgkmcnt(0)
	s_barrier
	s_setprio 1
	s_waitcnt lgkmcnt(0)
	v_mfma_f32_16x16x32_bf16 v[128:131], v[158:161], v[192:195], v[128:131]
	v_mfma_f32_16x16x32_bf16 v[124:127], v[168:171], v[192:195], v[124:127]
	v_mfma_f32_16x16x32_bf16 v[120:123], v[158:161], v[214:217], v[120:123]
	v_mfma_f32_16x16x32_bf16 v[112:115], v[168:171], v[214:217], v[112:115]
	v_mfma_f32_16x16x32_bf16 v[104:107], v[158:161], v[222:225], v[104:107]
	v_mfma_f32_16x16x32_bf16 v[96:99], v[168:171], v[222:225], v[96:99]
	v_mfma_f32_16x16x32_bf16 v[88:91], v[158:161], v[230:233], v[88:91]
	v_mfma_f32_16x16x32_bf16 v[80:83], v[168:171], v[230:233], v[80:83]
	v_mfma_f32_16x16x32_bf16 v[128:131], v[164:167], v[196:199], v[128:131]
	v_mfma_f32_16x16x32_bf16 v[124:127], v[172:175], v[196:199], v[124:127]
	v_mfma_f32_16x16x32_bf16 v[120:123], v[164:167], v[218:221], v[120:123]
	v_mfma_f32_16x16x32_bf16 v[112:115], v[172:175], v[218:221], v[112:115]
	v_mfma_f32_16x16x32_bf16 v[104:107], v[164:167], v[226:229], v[104:107]
	v_mfma_f32_16x16x32_bf16 v[96:99], v[172:175], v[226:229], v[96:99]
	v_mfma_f32_16x16x32_bf16 v[88:91], v[164:167], v[234:237], v[88:91]
	v_mfma_f32_16x16x32_bf16 v[80:83], v[172:175], v[234:237], v[80:83]
	s_setprio 0
	s_setprio 1
	v_mfma_f32_16x16x32_bf16 v[116:119], v[176:179], v[192:195], v[116:119]
	v_mfma_f32_16x16x32_bf16 v[108:111], v[184:187], v[192:195], v[108:111]
	v_mfma_f32_16x16x32_bf16 v[100:103], v[176:179], v[214:217], v[100:103]
	v_mfma_f32_16x16x32_bf16 v[92:95], v[184:187], v[214:217], v[92:95]
	v_mfma_f32_16x16x32_bf16 v[84:87], v[176:179], v[222:225], v[84:87]
	v_mfma_f32_16x16x32_bf16 v[76:79], v[184:187], v[222:225], v[76:79]
	v_mfma_f32_16x16x32_bf16 v[72:75], v[176:179], v[230:233], v[72:75]
	v_mfma_f32_16x16x32_bf16 v[68:71], v[184:187], v[230:233], v[68:71]
	v_mfma_f32_16x16x32_bf16 v[116:119], v[180:183], v[196:199], v[116:119]
	v_mfma_f32_16x16x32_bf16 v[108:111], v[188:191], v[196:199], v[108:111]
	v_mfma_f32_16x16x32_bf16 v[100:103], v[180:183], v[218:221], v[100:103]
	v_mfma_f32_16x16x32_bf16 v[92:95], v[188:191], v[218:221], v[92:95]
	v_mfma_f32_16x16x32_bf16 v[84:87], v[180:183], v[226:229], v[84:87]
	v_mfma_f32_16x16x32_bf16 v[76:79], v[188:191], v[226:229], v[76:79]
	v_mfma_f32_16x16x32_bf16 v[72:75], v[180:183], v[234:237], v[72:75]
	v_mfma_f32_16x16x32_bf16 v[68:71], v[188:191], v[234:237], v[68:71]
	s_setprio 0
	s_barrier
; #define PG8_STAGE(bufoff, gbase, voff) do { _Pragma("unroll") for (int _i = 0; _i < 2; ++_i) \
;         __builtin_amdgcn_global_load_lds((const unsigned*)((const char*)(gbase) + (voff)[_i]), (LAS unsigned*)(lds + (bufoff) + ldsw + _i * 8192), 16, 0, 0); } while (0)
; #define PG8_LDA(dst, b, h) do { _Pragma("unroll") for (int m = 0; m < 4; ++m) _Pragma("unroll") for (int k = 0; k < 2; ++k) dst[m][k] = *(const LAS bf16x8*)(lds + PG8_SA(b, h) + aoff + m * 2048 + k * 1024); } while (0)
; #define PG8_WAIT_V(n) asm volatile("s_waitcnt vmcnt(" #n ")" ::: "memory")
; #define PG8_WAIT_L(n) asm volatile("s_waitcnt lgkmcnt(" #n ")" ::: "memory")
; template <class Epi>
; __device__ __forceinline__ void gemm_phase(LAS unsigned char* lds, const Gemm g, const int G, const int cidx, const Epi& E) {
;     ...
;         const bool has_next = S.next(ui + 1, nxt);
;         const char* nA = has_next ? PG8_ABASE(nxt) : cA; const char* nB = has_next ? (const char*)g.Bt + (size_t)nxt.pn * tstep : cB;
;         for (int t = 0; t < nt; t += 2) {
;             const bool last = (t == nt - 2);
;             const char* a1 = cA + (size_t)(t + 1) * kstep;
;             const char* a2 = last ? nA : cA + (size_t)(t + 2) * kstep; const char* b2 = last ? nB : cB + (size_t)(t + 2) * kstep;
;             const char* a3 = a2 + kstep; const char* b3 = b2 + kstep;
;             PG8_LDB(B0, 0, 0); PG8_LDB(B1, 0, 1); PG8_SCHED; PG8_LDA(At, 0, 0); PG8_STAGE(PG8_SA(1, 1), a1 + hstep, voffA);
;             PG8_WAIT_V(8); PG8_WAIT_L(0); PG8_BAR; PG8_MMA(0, 0, At, B0); PG8_MMA(0, 1, At, B1); PG8_BAR; PG8_SCHED;
;             PG8_LDA(At, 0, 1); PG8_STAGE(PG8_SB(0, 0), b2, voffB); PG8_STAGE(PG8_SB(0, 1), b2 + hstep, voffB); PG8_STAGE(PG8_SA(0, 0), a2, voffA);
;             PG8_WAIT_V(8); PG8_WAIT_L(0); PG8_BAR; PG8_MMA(1, 0, At, B0); PG8_MMA(1, 1, At, B1); PG8_BAR; PG8_SCHED;
;             PG8_LDB(B0, 1, 0); PG8_LDB(B1, 1, 1); PG8_SCHED; PG8_LDA(At, 1, 0); PG8_STAGE(PG8_SA(0, 1), a2 + hstep, voffA);
;             PG8_WAIT_V(8); PG8_WAIT_L(0); PG8_BAR; PG8_MMA(0, 0, At, B0); PG8_MMA(0, 1, At, B1); PG8_BAR; PG8_SCHED;
;             PG8_LDA(At, 1, 1); PG8_STAGE(PG8_SB(1, 0), b3, voffB); PG8_STAGE(PG8_SB(1, 1), b3 + hstep, voffB); PG8_STAGE(PG8_SA(1, 0), a3, voffA);
;             PG8_WAIT_V(8); PG8_WAIT_L(0); PG8_BAR; PG8_MMA(1, 0, At, B0); PG8_MMA(1, 1, At, B1); PG8_BAR; PG8_SCHED;
	s_add_i32 s26, s43, s95
	s_add_u32 s100, s24, 0x80
	s_addc_u32 s101, s25, 0
	s_mov_b32 m0, s26
	ds_read_b128 v[192:195], v163 offset:49152
	ds_read_b128 v[196:199], v163 offset:50176
	ds_read_b128 v[214:217], v163 offset:51200
	ds_read_b128 v[218:221], v163 offset:52224
	ds_read_b128 v[222:225], v163 offset:53248
	ds_read_b128 v[226:229], v163 offset:54272
	ds_read_b128 v[230:233], v163 offset:55296
	ds_read_b128 v[234:237], v163 offset:56320
	global_load_lds_dwordx4 v148, s[100:101]
	s_add_i32 m0, s26, 0x2000
	s_add_i32 s26, s68, s95
	global_load_lds_dwordx4 v0, s[100:101]
	s_add_u32 s100, s100, 0x40000
	s_addc_u32 s101, s101, 0
	s_mov_b32 m0, s26
	s_nop 0
	global_load_lds_dwordx4 v148, s[100:101]
	s_add_i32 m0, s26, 0x2000
	s_nop 0
	global_load_lds_dwordx4 v0, s[100:101]
	s_mov_b32 m0, s84
	s_nop 0
	global_load_lds_dwordx4 v150, s[98:99]
	s_mov_b32 m0, s76
	s_nop 0
	global_load_lds_dwordx4 v146, s[98:99]
	s_waitcnt vmcnt(8)
	s_waitcnt lgkmcnt(0)
	s_barrier
	s_setprio 1
	s_waitcnt lgkmcnt(0)
	v_mfma_f32_16x16x32_bf16 v[64:67], v[158:161], v[192:195], v[64:67]
	v_mfma_f32_16x16x32_bf16 v[60:63], v[168:171], v[192:195], v[60:63]
	v_mfma_f32_16x16x32_bf16 v[56:59], v[158:161], v[214:217], v[56:59]
	v_mfma_f32_16x16x32_bf16 v[48:51], v[168:171], v[214:217], v[48:51]
	v_mfma_f32_16x16x32_bf16 v[40:43], v[158:161], v[222:225], v[40:43]
	v_mfma_f32_16x16x32_bf16 v[32:35], v[168:171], v[222:225], v[32:35]
	v_mfma_f32_16x16x32_bf16 v[24:27], v[158:161], v[230:233], v[24:27]
	v_mfma_f32_16x16x32_bf16 v[16:19], v[168:171], v[230:233], v[16:19]
	v_mfma_f32_16x16x32_bf16 v[64:67], v[164:167], v[196:199], v[64:67]
	v_mfma_f32_16x16x32_bf16 v[60:63], v[172:175], v[196:199], v[60:63]
	v_mfma_f32_16x16x32_bf16 v[56:59], v[164:167], v[218:221], v[56:59]
	v_mfma_f32_16x16x32_bf16 v[48:51], v[172:175], v[218:221], v[48:51]
	v_mfma_f32_16x16x32_bf16 v[40:43], v[164:167], v[226:229], v[40:43]
	v_mfma_f32_16x16x32_bf16 v[32:35], v[172:175], v[226:229], v[32:35]
	v_mfma_f32_16x16x32_bf16 v[24:27], v[164:167], v[234:237], v[24:27]
	v_mfma_f32_16x16x32_bf16 v[16:19], v[172:175], v[234:237], v[16:19]
	s_setprio 0
	s_setprio 1
	v_mfma_f32_16x16x32_bf16 v[52:55], v[176:179], v[192:195], v[52:55]
	v_mfma_f32_16x16x32_bf16 v[44:47], v[184:187], v[192:195], v[44:47]
	v_mfma_f32_16x16x32_bf16 v[36:39], v[176:179], v[214:217], v[36:39]
	v_mfma_f32_16x16x32_bf16 v[28:31], v[184:187], v[214:217], v[28:31]
	v_mfma_f32_16x16x32_bf16 v[20:23], v[176:179], v[222:225], v[20:23]
	v_mfma_f32_16x16x32_bf16 v[12:15], v[184:187], v[222:225], v[12:15]
	v_mfma_f32_16x16x32_bf16 v[8:11], v[176:179], v[230:233], v[8:11]
	v_mfma_f32_16x16x32_bf16 v[4:7], v[184:187], v[230:233], v[4:7]
	v_mfma_f32_16x16x32_bf16 v[52:55], v[180:183], v[196:199], v[52:55]
	v_mfma_f32_16x16x32_bf16 v[44:47], v[188:191], v[196:199], v[44:47]
	v_mfma_f32_16x16x32_bf16 v[36:39], v[180:183], v[218:221], v[36:39]
	v_mfma_f32_16x16x32_bf16 v[28:31], v[188:191], v[218:221], v[28:31]
	v_mfma_f32_16x16x32_bf16 v[20:23], v[180:183], v[226:229], v[20:23]
	v_mfma_f32_16x16x32_bf16 v[12:15], v[188:191], v[226:229], v[12:15]
	v_mfma_f32_16x16x32_bf16 v[8:11], v[180:183], v[234:237], v[8:11]
	v_mfma_f32_16x16x32_bf16 v[4:7], v[188:191], v[234:237], v[4:7]
	s_setprio 0
	s_barrier
	s_add_i32 s45, s45, 2
	s_add_u32 s42, s42, 0x100
	s_addc_u32 s44, s44, 0
	s_add_u32 s20, s20, 0x100
	s_addc_u32 s21, s21, 0
.LBB0_601:
	s_add_u32 s24, s20, 0xfffc0080
	s_addc_u32 s25, s21, -1
	s_add_i32 s43, 0, 0x10000
	s_cmp_eq_u32 s45, 12
	s_cselect_b32 s27, s11, s25
	s_cselect_b32 s26, s19, s24
	v_add_u32_e32 v132, s43, v145
	s_cselect_b32 s25, s9, s44
	s_cselect_b32 s24, s33, s42
	s_add_i32 s68, 0, 0x14000
	ds_read_b128 v[158:161], v132
	ds_read_b128 v[164:167], v132 offset:1024
	ds_read_b128 v[168:171], v132 offset:2048
	ds_read_b128 v[172:175], v132 offset:3072
	v_add_u32_e32 v132, s68, v145
	ds_read_b128 v[176:179], v132
	ds_read_b128 v[180:183], v132 offset:1024
	ds_read_b128 v[184:187], v132 offset:2048
	ds_read_b128 v[188:191], v132 offset:3072
	s_add_i32 m0, s97, 0xc000
	ds_read_b128 v[192:195], v163
	ds_read_b128 v[196:199], v163 offset:1024
	ds_read_b128 v[214:217], v163 offset:2048
	ds_read_b128 v[218:221], v163 offset:3072
	ds_read_b128 v[222:225], v163 offset:4096
	ds_read_b128 v[226:229], v163 offset:5120
	ds_read_b128 v[230:233], v163 offset:6144
	ds_read_b128 v[234:237], v163 offset:7168
	global_load_lds_dwordx4 v156, s[20:21]
	s_add_i32 m0, s97, 0xe000
	s_nop 0
	global_load_lds_dwordx4 v154, s[20:21]
	s_waitcnt vmcnt(8)
	s_waitcnt lgkmcnt(0)
	s_barrier
; #define PG8_STAGE(bufoff, gbase, voff) do { _Pragma("unroll") for (int _i = 0; _i < 2; ++_i) \
;         __builtin_amdgcn_global_load_lds((const unsigned*)((const char*)(gbase) + (voff)[_i]), (LAS unsigned*)(lds + (bufoff) + ldsw + _i * 8192), 16, 0, 0); } while (0)
; #define PG8_LDA(dst, b, h) do { _Pragma("unroll") for (int m = 0; m < 4; ++m) _Pragma("unroll") for (int k = 0; k < 2; ++k) dst[m][k] = *(const LAS bf16x8*)(lds + PG8_SA(b, h) + aoff + m * 2048 + k * 1024); } while (0)
; #define PG8_LDB(dst, b, h) do { _Pragma("unroll") for (int n = 0; n < 2; ++n) _Pragma("unroll") for (int k = 0; k < 2; ++k) dst[n][k] = *(const LAS bf16x8*)(lds + PG8_SB(b, h) + boff + n * 2048 + k * 1024); } while (0)
; #define PG8_MMA(ai, bj, At, Bt) do { __builtin_amdgcn_s_setprio(1); _Pragma("unroll") for (int m = 0; m < 4; ++m) _Pragma("unroll") for (int n = 0; n < 2; ++n) _Pragma("unroll") for (int k = 0; k < 2; ++k) \
;         acc[ai][bj][m][n] = __builtin_amdgcn_mfma_f32_16x16x32_bf16(Bt[n][k], At[m][k], acc[ai][bj][m][n], 0, 0, 0); __builtin_amdgcn_s_setprio(0); } while (0)
; #define PG8_WAIT_V(n) asm volatile("s_waitcnt vmcnt(" #n ")" ::: "memory")
; #define PG8_BAR __builtin_amdgcn_s_barrier()
; template <class Epi>
; __device__ __forceinline__ void gemm_phase(LAS unsigned char* lds, const Gemm g, const int G, const int cidx, const Epi& E) {
;     ...
;             PG8_LDB(B0, 0, 0); PG8_LDB(B1, 0, 1); PG8_SCHED; PG8_LDA(At, 0, 0); PG8_STAGE(PG8_SA(1, 1), a1 + hstep, voffA);
;             PG8_WAIT_V(8); PG8_WAIT_L(0); PG8_BAR; PG8_MMA(0, 0, At, B0); PG8_MMA(0, 1, At, B1); PG8_BAR; PG8_SCHED;
;             PG8_LDA(At, 0, 1); PG8_STAGE(PG8_SB(0, 0), b2, voffB); PG8_STAGE(PG8_SB(0, 1), b2 + hstep, voffB); PG8_STAGE(PG8_SA(0, 0), a2, voffA);
;             PG8_WAIT_V(8); PG8_WAIT_L(0); PG8_BAR; PG8_MMA(1, 0, At, B0); PG8_MMA(1, 1, At, B1); PG8_BAR; PG8_SCHED;
;             PG8_LDB(B0, 1, 0); PG8_LDB(B1, 1, 1); PG8_SCHED; PG8_LDA(At, 1, 0); PG8_STAGE(PG8_SA(0, 1), a2 + hstep, voffA);
;             PG8_WAIT_V(8); PG8_WAIT_L(0); PG8_BAR; PG8_MMA(0, 0, At, B0); PG8_MMA(0, 1, At, B1); PG8_BAR; PG8_SCHED;
;             PG8_LDA(At, 1, 1); PG8_STAGE(PG8_SB(1, 0), b3, voffB); PG8_STAGE(PG8_SB(1, 1), b3 + hstep, voffB); PG8_STAGE(PG8_SA(1, 0), a3, voffA);
;             PG8_WAIT_V(8); PG8_WAIT_L(0); PG8_BAR; PG8_MMA(1, 0, At, B0); PG8_MMA(1, 1, At, B1); PG8_BAR; PG8_SCHED;
	s_setprio 1
	s_waitcnt lgkmcnt(0)
	v_mfma_f32_16x16x32_bf16 v[128:131], v[158:161], v[192:195], v[128:131]
	v_mfma_f32_16x16x32_bf16 v[124:127], v[168:171], v[192:195], v[124:127]
	v_mfma_f32_16x16x32_bf16 v[120:123], v[158:161], v[214:217], v[120:123]
	v_mfma_f32_16x16x32_bf16 v[112:115], v[168:171], v[214:217], v[112:115]
	v_mfma_f32_16x16x32_bf16 v[104:107], v[158:161], v[222:225], v[104:107]
	v_mfma_f32_16x16x32_bf16 v[96:99], v[168:171], v[222:225], v[96:99]
	v_mfma_f32_16x16x32_bf16 v[88:91], v[158:161], v[230:233], v[88:91]
	v_mfma_f32_16x16x32_bf16 v[80:83], v[168:171], v[230:233], v[80:83]
	v_mfma_f32_16x16x32_bf16 v[128:131], v[164:167], v[196:199], v[128:131]
	v_mfma_f32_16x16x32_bf16 v[124:127], v[172:175], v[196:199], v[124:127]
	v_mfma_f32_16x16x32_bf16 v[120:123], v[164:167], v[218:221], v[120:123]
	v_mfma_f32_16x16x32_bf16 v[112:115], v[172:175], v[218:221], v[112:115]
	v_mfma_f32_16x16x32_bf16 v[104:107], v[164:167], v[226:229], v[104:107]
	v_mfma_f32_16x16x32_bf16 v[96:99], v[172:175], v[226:229], v[96:99]
	v_mfma_f32_16x16x32_bf16 v[88:91], v[164:167], v[234:237], v[88:91]
	v_mfma_f32_16x16x32_bf16 v[80:83], v[172:175], v[234:237], v[80:83]
	s_setprio 0
	s_setprio 1
	v_mfma_f32_16x16x32_bf16 v[116:119], v[176:179], v[192:195], v[116:119]
	v_mfma_f32_16x16x32_bf16 v[108:111], v[184:187], v[192:195], v[108:111]
	v_mfma_f32_16x16x32_bf16 v[100:103], v[176:179], v[214:217], v[100:103]
	v_mfma_f32_16x16x32_bf16 v[92:95], v[184:187], v[214:217], v[92:95]
	v_mfma_f32_16x16x32_bf16 v[84:87], v[176:179], v[222:225], v[84:87]
	v_mfma_f32_16x16x32_bf16 v[76:79], v[184:187], v[222:225], v[76:79]
	v_mfma_f32_16x16x32_bf16 v[72:75], v[176:179], v[230:233], v[72:75]
	v_mfma_f32_16x16x32_bf16 v[68:71], v[184:187], v[230:233], v[68:71]
	v_mfma_f32_16x16x32_bf16 v[116:119], v[180:183], v[196:199], v[116:119]
	v_mfma_f32_16x16x32_bf16 v[108:111], v[188:191], v[196:199], v[108:111]
	v_mfma_f32_16x16x32_bf16 v[100:103], v[180:183], v[218:221], v[100:103]
	v_mfma_f32_16x16x32_bf16 v[92:95], v[188:191], v[218:221], v[92:95]
	v_mfma_f32_16x16x32_bf16 v[84:87], v[180:183], v[226:229], v[84:87]
	v_mfma_f32_16x16x32_bf16 v[76:79], v[188:191], v[226:229], v[76:79]
	v_mfma_f32_16x16x32_bf16 v[72:75], v[180:183], v[234:237], v[72:75]
	v_mfma_f32_16x16x32_bf16 v[68:71], v[188:191], v[234:237], v[68:71]
	s_setprio 0
	s_barrier
	s_add_i32 s43, s43, s95
	s_mov_b32 m0, s43
	ds_read_b128 v[192:195], v163 offset:16384
	ds_read_b128 v[196:199], v163 offset:17408
	ds_read_b128 v[214:217], v163 offset:18432
	ds_read_b128 v[218:221], v163 offset:19456
	ds_read_b128 v[222:225], v163 offset:20480
	ds_read_b128 v[226:229], v163 offset:21504
	ds_read_b128 v[230:233], v163 offset:22528
	ds_read_b128 v[234:237], v163 offset:23552
	global_load_lds_dwordx4 v148, s[24:25]
	s_add_i32 m0, s43, 0x2000
	s_add_u32 s86, s24, 0x40000
	s_addc_u32 s87, s25, 0
	s_add_i32 s43, s68, s95
	global_load_lds_dwordx4 v0, s[24:25]
	s_mov_b32 m0, s43
	s_nop 0
	global_load_lds_dwordx4 v148, s[86:87]
	s_add_i32 m0, s43, 0x2000
	s_nop 0
	global_load_lds_dwordx4 v0, s[86:87]
	s_mov_b32 m0, s97
	s_nop 0
	global_load_lds_dwordx4 v150, s[26:27]
	s_mov_b32 m0, s22
	s_nop 0
	global_load_lds_dwordx4 v146, s[26:27]
	s_waitcnt vmcnt(8)
	s_waitcnt lgkmcnt(0)
	s_barrier
	s_setprio 1
	s_waitcnt lgkmcnt(0)
	v_mfma_f32_16x16x32_bf16 v[64:67], v[158:161], v[192:195], v[64:67]
	v_mfma_f32_16x16x32_bf16 v[60:63], v[168:171], v[192:195], v[60:63]
	v_mfma_f32_16x16x32_bf16 v[56:59], v[158:161], v[214:217], v[56:59]
	v_mfma_f32_16x16x32_bf16 v[48:51], v[168:171], v[214:217], v[48:51]
	v_mfma_f32_16x16x32_bf16 v[40:43], v[158:161], v[222:225], v[40:43]
	v_mfma_f32_16x16x32_bf16 v[32:35], v[168:171], v[222:225], v[32:35]
	v_mfma_f32_16x16x32_bf16 v[24:27], v[158:161], v[230:233], v[24:27]
	v_mfma_f32_16x16x32_bf16 v[16:19], v[168:171], v[230:233], v[16:19]
	v_mfma_f32_16x16x32_bf16 v[64:67], v[164:167], v[196:199], v[64:67]
	v_mfma_f32_16x16x32_bf16 v[60:63], v[172:175], v[196:199], v[60:63]
	v_mfma_f32_16x16x32_bf16 v[56:59], v[164:167], v[218:221], v[56:59]
	v_mfma_f32_16x16x32_bf16 v[48:51], v[172:175], v[218:221], v[48:51]
	v_mfma_f32_16x16x32_bf16 v[40:43], v[164:167], v[226:229], v[40:43]
	v_mfma_f32_16x16x32_bf16 v[32:35], v[172:175], v[226:229], v[32:35]
	v_mfma_f32_16x16x32_bf16 v[24:27], v[164:167], v[234:237], v[24:27]
	v_mfma_f32_16x16x32_bf16 v[16:19], v[172:175], v[234:237], v[16:19]
	s_setprio 0
	s_setprio 1
	v_mfma_f32_16x16x32_bf16 v[52:55], v[176:179], v[192:195], v[52:55]
	v_mfma_f32_16x16x32_bf16 v[44:47], v[184:187], v[192:195], v[44:47]
	v_mfma_f32_16x16x32_bf16 v[36:39], v[176:179], v[214:217], v[36:39]
	v_mfma_f32_16x16x32_bf16 v[28:31], v[184:187], v[214:217], v[28:31]
	v_mfma_f32_16x16x32_bf16 v[20:23], v[176:179], v[222:225], v[20:23]
	v_mfma_f32_16x16x32_bf16 v[12:15], v[184:187], v[222:225], v[12:15]
	v_mfma_f32_16x16x32_bf16 v[8:11], v[176:179], v[230:233], v[8:11]
	v_mfma_f32_16x16x32_bf16 v[4:7], v[184:187], v[230:233], v[4:7]
	v_mfma_f32_16x16x32_bf16 v[52:55], v[180:183], v[196:199], v[52:55]
	v_mfma_f32_16x16x32_bf16 v[44:47], v[188:191], v[196:199], v[44:47]
	v_mfma_f32_16x16x32_bf16 v[36:39], v[180:183], v[218:221], v[36:39]
	v_mfma_f32_16x16x32_bf16 v[28:31], v[188:191], v[218:221], v[28:31]
	v_mfma_f32_16x16x32_bf16 v[20:23], v[180:183], v[226:229], v[20:23]
	v_mfma_f32_16x16x32_bf16 v[12:15], v[188:191], v[226:229], v[12:15]
	v_mfma_f32_16x16x32_bf16 v[8:11], v[180:183], v[234:237], v[8:11]
	v_mfma_f32_16x16x32_bf16 v[4:7], v[188:191], v[234:237], v[4:7]
	s_setprio 0
	s_barrier
; #define PG8_STAGE(bufoff, gbase, voff) do { _Pragma("unroll") for (int _i = 0; _i < 2; ++_i) \
;         __builtin_amdgcn_global_load_lds((const unsigned*)((const char*)(gbase) + (voff)[_i]), (LAS unsigned*)(lds + (bufoff) + ldsw + _i * 8192), 16, 0, 0); } while (0)
; #define PG8_LDA(dst, b, h) do { _Pragma("unroll") for (int m = 0; m < 4; ++m) _Pragma("unroll") for (int k = 0; k < 2; ++k) dst[m][k] = *(const LAS bf16x8*)(lds + PG8_SA(b, h) + aoff + m * 2048 + k * 1024); } while (0)
; #define PG8_LDB(dst, b, h) do { _Pragma("unroll") for (int n = 0; n < 2; ++n) _Pragma("unroll") for (int k = 0; k < 2; ++k) dst[n][k] = *(const LAS bf16x8*)(lds + PG8_SB(b, h) + boff + n * 2048 + k * 1024); } while (0)
; #define PG8_MMA(ai, bj, At, Bt) do { __builtin_amdgcn_s_setprio(1); _Pragma("unroll") for (int m = 0; m < 4; ++m) _Pragma("unroll") for (int n = 0; n < 2; ++n) _Pragma("unroll") for (int k = 0; k < 2; ++k) \
;         acc[ai][bj][m][n] = __builtin_amdgcn_mfma_f32_16x16x32_bf16(Bt[n][k], At[m][k], acc[ai][bj][m][n], 0, 0, 0); __builtin_amdgcn_s_setprio(0); } while (0)
; #define PG8_WAIT_V(n) asm volatile("s_waitcnt vmcnt(" #n ")" ::: "memory")
; #define PG8_WAIT_L(n) asm volatile("s_waitcnt lgkmcnt(" #n ")" ::: "memory")
; #define PG8_BAR __builtin_amdgcn_s_barrier()
; #define PG8_SCHED __builtin_amdgcn_sched_barrier(0)
; template <class Epi>
; __device__ __forceinline__ void gemm_phase(LAS unsigned char* lds, const Gemm g, const int G, const int cidx, const Epi& E) {
;     ...
;             PG8_LDB(B0, 1, 0); PG8_LDB(B1, 1, 1); PG8_SCHED; PG8_LDA(At, 1, 0); PG8_STAGE(PG8_SA(0, 1), a2 + hstep, voffA);
;             PG8_WAIT_V(8); PG8_WAIT_L(0); PG8_BAR; PG8_MMA(0, 0, At, B0); PG8_MMA(0, 1, At, B1); PG8_BAR; PG8_SCHED;
;             PG8_LDA(At, 1, 1); PG8_STAGE(PG8_SB(1, 0), b3, voffB); PG8_STAGE(PG8_SB(1, 1), b3 + hstep, voffB); PG8_STAGE(PG8_SA(1, 0), a3, voffA);
;             PG8_WAIT_V(8); PG8_WAIT_L(0); PG8_BAR; PG8_MMA(1, 0, At, B0); PG8_MMA(1, 1, At, B1); PG8_BAR; PG8_SCHED;
	s_add_i32 s43, 0, 0x18000
	s_add_i32 s68, 0, 0x1c000
	v_add_u32_e32 v172, s43, v145
	v_add_u32_e32 v188, s68, v145
	ds_read_b128 v[158:161], v172
	ds_read_b128 v[164:167], v172 offset:1024
	ds_read_b128 v[168:171], v172 offset:2048
	ds_read_b128 v[172:175], v172 offset:3072
	ds_read_b128 v[176:179], v188
	ds_read_b128 v[180:183], v188 offset:1024
	ds_read_b128 v[184:187], v188 offset:2048
	ds_read_b128 v[188:191], v188 offset:3072
	s_add_u32 s98, s26, 0x80
	s_addc_u32 s99, s27, 0
	s_add_u32 s26, s26, 0x40000
	s_addc_u32 s27, s27, 0
	s_mov_b32 m0, s16
	ds_read_b128 v[192:195], v163 offset:32768
	ds_read_b128 v[196:199], v163 offset:33792
	ds_read_b128 v[214:217], v163 offset:34816
	ds_read_b128 v[218:221], v163 offset:35840
	ds_read_b128 v[222:225], v163 offset:36864
	ds_read_b128 v[226:229], v163 offset:37888
	ds_read_b128 v[230:233], v163 offset:38912
	ds_read_b128 v[234:237], v163 offset:39936
	global_load_lds_dwordx4 v150, s[26:27]
	s_mov_b32 m0, s17
	s_nop 0
	global_load_lds_dwordx4 v146, s[26:27]
	s_waitcnt vmcnt(8)
	s_waitcnt lgkmcnt(0)
	s_barrier
	s_setprio 1
	s_waitcnt lgkmcnt(0)
	v_mfma_f32_16x16x32_bf16 v[128:131], v[158:161], v[192:195], v[128:131]
	v_mfma_f32_16x16x32_bf16 v[124:127], v[168:171], v[192:195], v[124:127]
	v_mfma_f32_16x16x32_bf16 v[120:123], v[158:161], v[214:217], v[120:123]
	v_mfma_f32_16x16x32_bf16 v[112:115], v[168:171], v[214:217], v[112:115]
	v_mfma_f32_16x16x32_bf16 v[104:107], v[158:161], v[222:225], v[104:107]
	v_mfma_f32_16x16x32_bf16 v[96:99], v[168:171], v[222:225], v[96:99]
	v_mfma_f32_16x16x32_bf16 v[88:91], v[158:161], v[230:233], v[88:91]
	v_mfma_f32_16x16x32_bf16 v[80:83], v[168:171], v[230:233], v[80:83]
	v_mfma_f32_16x16x32_bf16 v[128:131], v[164:167], v[196:199], v[128:131]
	v_mfma_f32_16x16x32_bf16 v[124:127], v[172:175], v[196:199], v[124:127]
	v_mfma_f32_16x16x32_bf16 v[120:123], v[164:167], v[218:221], v[120:123]
	v_mfma_f32_16x16x32_bf16 v[112:115], v[172:175], v[218:221], v[112:115]
	v_mfma_f32_16x16x32_bf16 v[104:107], v[164:167], v[226:229], v[104:107]
	v_mfma_f32_16x16x32_bf16 v[96:99], v[172:175], v[226:229], v[96:99]
	v_mfma_f32_16x16x32_bf16 v[88:91], v[164:167], v[234:237], v[88:91]
	v_mfma_f32_16x16x32_bf16 v[80:83], v[172:175], v[234:237], v[80:83]
	s_setprio 0
	s_setprio 1
	v_mfma_f32_16x16x32_bf16 v[116:119], v[176:179], v[192:195], v[116:119]
	v_mfma_f32_16x16x32_bf16 v[108:111], v[184:187], v[192:195], v[108:111]
	v_mfma_f32_16x16x32_bf16 v[100:103], v[176:179], v[214:217], v[100:103]
	v_mfma_f32_16x16x32_bf16 v[92:95], v[184:187], v[214:217], v[92:95]
	v_mfma_f32_16x16x32_bf16 v[84:87], v[176:179], v[222:225], v[84:87]
	v_mfma_f32_16x16x32_bf16 v[76:79], v[184:187], v[222:225], v[76:79]
	v_mfma_f32_16x16x32_bf16 v[72:75], v[176:179], v[230:233], v[72:75]
	v_mfma_f32_16x16x32_bf16 v[68:71], v[184:187], v[230:233], v[68:71]
	v_mfma_f32_16x16x32_bf16 v[116:119], v[180:183], v[196:199], v[116:119]
	v_mfma_f32_16x16x32_bf16 v[108:111], v[188:191], v[196:199], v[108:111]
	v_mfma_f32_16x16x32_bf16 v[100:103], v[180:183], v[218:221], v[100:103]
	v_mfma_f32_16x16x32_bf16 v[92:95], v[188:191], v[218:221], v[92:95]
	v_mfma_f32_16x16x32_bf16 v[84:87], v[180:183], v[226:229], v[84:87]
	v_mfma_f32_16x16x32_bf16 v[76:79], v[188:191], v[226:229], v[76:79]
	v_mfma_f32_16x16x32_bf16 v[72:75], v[180:183], v[234:237], v[72:75]
	v_mfma_f32_16x16x32_bf16 v[68:71], v[188:191], v[234:237], v[68:71]
	s_setprio 0
	s_barrier
	s_add_i32 s26, s43, s95
	s_add_u32 s100, s24, 0x80
	s_addc_u32 s101, s25, 0
	s_mov_b32 m0, s26
	ds_read_b128 v[192:195], v163 offset:49152
	ds_read_b128 v[196:199], v163 offset:50176
	ds_read_b128 v[214:217], v163 offset:51200
	ds_read_b128 v[218:221], v163 offset:52224
	ds_read_b128 v[222:225], v163 offset:53248
	ds_read_b128 v[226:229], v163 offset:54272
	ds_read_b128 v[230:233], v163 offset:55296
	ds_read_b128 v[234:237], v163 offset:56320
	global_load_lds_dwordx4 v148, s[100:101]
	s_add_i32 m0, s26, 0x2000
	s_add_i32 s26, s68, s95
	global_load_lds_dwordx4 v0, s[100:101]
	s_add_u32 s100, s100, 0x40000
	s_addc_u32 s101, s101, 0
	s_mov_b32 m0, s26
	s_nop 0
	global_load_lds_dwordx4 v148, s[100:101]
	s_add_i32 m0, s26, 0x2000
	s_nop 0
	global_load_lds_dwordx4 v0, s[100:101]
	s_mov_b32 m0, s84
	s_nop 0
	global_load_lds_dwordx4 v150, s[98:99]
	s_mov_b32 m0, s76
	s_nop 0
	global_load_lds_dwordx4 v146, s[98:99]
	s_waitcnt vmcnt(8)
	s_waitcnt lgkmcnt(0)
	s_barrier
	s_setprio 1
	s_waitcnt lgkmcnt(0)
	v_mfma_f32_16x16x32_bf16 v[64:67], v[158:161], v[192:195], v[64:67]
	v_mfma_f32_16x16x32_bf16 v[60:63], v[168:171], v[192:195], v[60:63]
	v_mfma_f32_16x16x32_bf16 v[56:59], v[158:161], v[214:217], v[56:59]
	v_mfma_f32_16x16x32_bf16 v[48:51], v[168:171], v[214:217], v[48:51]
	v_mfma_f32_16x16x32_bf16 v[40:43], v[158:161], v[222:225], v[40:43]
	v_mfma_f32_16x16x32_bf16 v[32:35], v[168:171], v[222:225], v[32:35]
	v_mfma_f32_16x16x32_bf16 v[24:27], v[158:161], v[230:233], v[24:27]
	v_mfma_f32_16x16x32_bf16 v[16:19], v[168:171], v[230:233], v[16:19]
	v_mfma_f32_16x16x32_bf16 v[64:67], v[164:167], v[196:199], v[64:67]
	v_mfma_f32_16x16x32_bf16 v[60:63], v[172:175], v[196:199], v[60:63]
	v_mfma_f32_16x16x32_bf16 v[56:59], v[164:167], v[218:221], v[56:59]
	v_mfma_f32_16x16x32_bf16 v[48:51], v[172:175], v[218:221], v[48:51]
	v_mfma_f32_16x16x32_bf16 v[40:43], v[164:167], v[226:229], v[40:43]
	v_mfma_f32_16x16x32_bf16 v[32:35], v[172:175], v[226:229], v[32:35]
	v_mfma_f32_16x16x32_bf16 v[24:27], v[164:167], v[234:237], v[24:27]
	v_mfma_f32_16x16x32_bf16 v[16:19], v[172:175], v[234:237], v[16:19]
	s_setprio 0
	s_setprio 1
	v_mfma_f32_16x16x32_bf16 v[52:55], v[176:179], v[192:195], v[52:55]
	v_mfma_f32_16x16x32_bf16 v[44:47], v[184:187], v[192:195], v[44:47]
	v_mfma_f32_16x16x32_bf16 v[36:39], v[176:179], v[214:217], v[36:39]
	v_mfma_f32_16x16x32_bf16 v[28:31], v[184:187], v[214:217], v[28:31]
	v_mfma_f32_16x16x32_bf16 v[20:23], v[176:179], v[222:225], v[20:23]
	v_mfma_f32_16x16x32_bf16 v[12:15], v[184:187], v[222:225], v[12:15]
	v_mfma_f32_16x16x32_bf16 v[8:11], v[176:179], v[230:233], v[8:11]
	v_mfma_f32_16x16x32_bf16 v[4:7], v[184:187], v[230:233], v[4:7]
	v_mfma_f32_16x16x32_bf16 v[52:55], v[180:183], v[196:199], v[52:55]
	v_mfma_f32_16x16x32_bf16 v[44:47], v[188:191], v[196:199], v[44:47]
	v_mfma_f32_16x16x32_bf16 v[36:39], v[180:183], v[218:221], v[36:39]
	v_mfma_f32_16x16x32_bf16 v[28:31], v[188:191], v[218:221], v[28:31]
	v_mfma_f32_16x16x32_bf16 v[20:23], v[180:183], v[226:229], v[20:23]
	v_mfma_f32_16x16x32_bf16 v[12:15], v[188:191], v[226:229], v[12:15]
	v_mfma_f32_16x16x32_bf16 v[8:11], v[180:183], v[234:237], v[8:11]
	v_mfma_f32_16x16x32_bf16 v[4:7], v[188:191], v[234:237], v[4:7]
	s_setprio 0
	s_barrier
; __device__ __forceinline__ unsigned pk2(float lo, float hi) { unsigned r; asm("v_cvt_pk_bf16_f32 %0, %1, %2" : "=v"(r) : "v"(lo), "v"(hi)); return r; }
;     __device__ __forceinline__ void operator()(const f32x4 (&acc)[2][2][4][2], const Unit& u, int wr, int wc, int fr, int fq) const {
;         if (u.pn < 11) {
;             const int row0 = u.pm * BM + wr * 64 + fr, col0 = u.pn * BM + wc * 32 + 8 * fq;
; #pragma unroll
;             for (int ai = 0; ai < 2; ++ai)
; #pragma unroll
;                 for (int m = 0; m < 4; ++m) { bf16_t* rowp = O + (size_t)(row0 + ai * HALF + m * 16) * ZLD + col0;
; #pragma unroll
;                     for (int bj = 0; bj < 2; ++bj) { const f32x4 v0 = acc[ai][bj][m][0], v1 = acc[ai][bj][m][1];
;                         u32x4 w; w.x = pk2(v0[0], v0[1]); w.y = pk2(v0[2], v0[3]); w.z = pk2(v1[0], v1[1]); w.w = pk2(v1[2], v1[3]);
;                         *(u32x4*)(rowp + bj * HALF) = w; } }
;         } else {
;             const int g = u.pn - 11, n = g >> 2, q = g & 3;
;             bf16_t* blk = Gt + (((size_t)n * 64 + u.pm) * 8 + q * 2) * 32768 + (size_t)((wr * 4 * 4 + wc) * 64 + fq * 16 + fr) * 8;
; #pragma unroll
;             for (int ai = 0; ai < 2; ++ai)
; #pragma unroll
;                 for (int m = 0; m < 4; ++m)
; #pragma unroll
;                     for (int bj = 0; bj < 2; ++bj) { const f32x4 v0 = acc[ai][bj][m][0], v1 = acc[ai][bj][m][1];
;                         u32x4 w; w.x = pk2(v0[0], v0[1]); w.y = pk2(v0[2], v0[3]); w.z = pk2(v1[0], v1[1]); w.w = pk2(v1[2], v1[3]);
;                         *(u32x4*)(blk + (size_t)bj * 32768 + (size_t)((ai * 8 + m) * 4) * 512) = w; }
;         }
; template <class Epi>
; __device__ __forceinline__ void gemm_phase(LAS unsigned char* lds, const Gemm g, const int G, const int cidx, const Epi& E) {
;     ...
;         }
;         if constexpr (!Epi::AFTER_DRAIN) E(acc, cur, wr, wc, fr, fq);
;         if (!has_next) break;
	s_add_i32 s45, s45, 2
	s_add_u32 s42, s42, 0x100
	s_addc_u32 s44, s44, 0
	s_add_u32 s20, s20, 0x100
	s_addc_u32 s21, s21, 0
	s_cmp_gt_u32 s45, 13
	s_cbranch_scc0 .LBB0_601
	s_cmp_gt_i32 s35, 10
	s_mov_b64 s[20:21], -1
	s_mov_b32 s26, 0x1a000
	s_mov_b32 s27, 0x19000
	s_cbranch_scc0 .LBB0_604
	s_add_i32 s9, s35, -11
	s_mov_b32 s21, s77
	s_lshr_b32 s20, s9, 2
	s_ashr_i32 s19, s18, 31
	s_lshl_b64 s[20:21], s[20:21], 9
	s_lshl_b64 s[24:25], s[18:19], 3
	s_add_u32 s11, s20, s24
	s_addc_u32 s21, s21, s25
	s_lshl_b32 s9, s9, 1
	s_and_b32 s9, s9, 6
	s_or_b32 s20, s11, s9
	s_lshl_b64 s[20:21], s[20:21], 16
	v_lshl_add_u64 v[158:159], v[152:153], 0, s[20:21]
	s_mov_b32 s9, 0x11000
	v_add_co_u32_e32 v132, vcc, s9, v158
	v_cvt_pk_bf16_f32 v164, v128, v129
	v_cvt_pk_bf16_f32 v165, v130, v131
	v_cvt_pk_bf16_f32 v166, v124, v125
	v_cvt_pk_bf16_f32 v167, v126, v127
	s_nop 1
	v_addc_co_u32_e32 v133, vcc, 0, v159, vcc
	global_store_dwordx4 v[158:159], v[164:167], off
	v_add_co_u32_e32 v134, vcc, s81, v158
	s_nop 0
	v_cvt_pk_bf16_f32 v164, v116, v117
	v_cvt_pk_bf16_f32 v165, v118, v119
	v_cvt_pk_bf16_f32 v166, v108, v109
	v_cvt_pk_bf16_f32 v167, v110, v111
	global_store_dwordx4 v[132:133], v[164:167], off offset:-4096
	v_addc_co_u32_e32 v135, vcc, 0, v159, vcc
	s_nop 0
	v_cvt_pk_bf16_f32 v164, v120, v121
	v_cvt_pk_bf16_f32 v165, v122, v123
	v_cvt_pk_bf16_f32 v166, v112, v113
	v_cvt_pk_bf16_f32 v167, v114, v115
	s_mov_b32 s9, 0x13000
	global_store_dwordx4 v[134:135], v[164:167], off offset:-4096
	s_mov_b64 s[20:21], 0
	s_nop 0
	v_cvt_pk_bf16_f32 v164, v100, v101
	v_cvt_pk_bf16_f32 v165, v102, v103
	v_cvt_pk_bf16_f32 v166, v92, v93
	v_cvt_pk_bf16_f32 v167, v94, v95
	global_store_dwordx4 v[132:133], v[164:167], off
	v_add_co_u32_e32 v132, vcc, s9, v158
	s_nop 0
	v_cvt_pk_bf16_f32 v164, v104, v105
	v_cvt_pk_bf16_f32 v165, v106, v107
	v_cvt_pk_bf16_f32 v166, v96, v97
	v_cvt_pk_bf16_f32 v167, v98, v99
	s_nop 0
	v_addc_co_u32_e32 v133, vcc, 0, v159, vcc
	global_store_dwordx4 v[134:135], v[164:167], off
	v_add_co_u32_e32 v134, vcc, s82, v158
	s_nop 0
	v_cvt_pk_bf16_f32 v164, v84, v85
	v_cvt_pk_bf16_f32 v165, v86, v87
	v_cvt_pk_bf16_f32 v166, v76, v77
	v_cvt_pk_bf16_f32 v167, v78, v79
	global_store_dwordx4 v[132:133], v[164:167], off offset:-4096
	v_addc_co_u32_e32 v135, vcc, 0, v159, vcc
	s_nop 0
	v_cvt_pk_bf16_f32 v164, v88, v89
	v_cvt_pk_bf16_f32 v165, v90, v91
	v_cvt_pk_bf16_f32 v166, v80, v81
	v_cvt_pk_bf16_f32 v167, v82, v83
	s_mov_b32 s9, 0x9000
	global_store_dwordx4 v[134:135], v[164:167], off
	s_nop 1
	v_cvt_pk_bf16_f32 v164, v72, v73
	v_cvt_pk_bf16_f32 v165, v74, v75
	v_cvt_pk_bf16_f32 v166, v68, v69
	v_cvt_pk_bf16_f32 v167, v70, v71
	global_store_dwordx4 v[132:133], v[164:167], off
	v_add_co_u32_e32 v132, vcc, s9, v158
	s_nop 0
	v_cvt_pk_bf16_f32 v164, v64, v65
	v_cvt_pk_bf16_f32 v165, v66, v67
	v_cvt_pk_bf16_f32 v166, v60, v61
	v_cvt_pk_bf16_f32 v167, v62, v63
	s_nop 0
	v_addc_co_u32_e32 v133, vcc, 0, v159, vcc
	v_add_co_u32_e32 v134, vcc, s27, v158
	global_store_dwordx4 v[132:133], v[164:167], off offset:-4096
	s_nop 0
	v_addc_co_u32_e32 v135, vcc, 0, v159, vcc
	v_cvt_pk_bf16_f32 v164, v52, v53
	v_cvt_pk_bf16_f32 v165, v54, v55
	v_cvt_pk_bf16_f32 v166, v44, v45
	v_cvt_pk_bf16_f32 v167, v46, v47
	s_mov_b32 s9, 0xb000
	global_store_dwordx4 v[134:135], v[164:167], off offset:-4096
	s_nop 1
	v_cvt_pk_bf16_f32 v164, v56, v57
	v_cvt_pk_bf16_f32 v165, v58, v59
	v_cvt_pk_bf16_f32 v166, v48, v49
	v_cvt_pk_bf16_f32 v167, v50, v51
	global_store_dwordx4 v[132:133], v[164:167], off
	v_add_co_u32_e32 v132, vcc, s9, v158
	s_nop 0
	v_cvt_pk_bf16_f32 v164, v36, v37
	v_cvt_pk_bf16_f32 v165, v38, v39
	v_cvt_pk_bf16_f32 v166, v28, v29
	v_cvt_pk_bf16_f32 v167, v30, v31
	s_nop 0
	v_addc_co_u32_e32 v133, vcc, 0, v159, vcc
	global_store_dwordx4 v[134:135], v[164:167], off
	v_add_co_u32_e32 v134, vcc, s26, v158
	s_nop 0
	v_cvt_pk_bf16_f32 v164, v40, v41
	v_cvt_pk_bf16_f32 v165, v42, v43
	v_cvt_pk_bf16_f32 v166, v32, v33
	v_cvt_pk_bf16_f32 v167, v34, v35
	global_store_dwordx4 v[132:133], v[164:167], off offset:-4096
	v_addc_co_u32_e32 v135, vcc, 0, v159, vcc
	s_nop 0
	v_cvt_pk_bf16_f32 v164, v20, v21
	v_cvt_pk_bf16_f32 v165, v22, v23
	v_cvt_pk_bf16_f32 v166, v12, v13
	v_cvt_pk_bf16_f32 v167, v14, v15
	global_store_dwordx4 v[134:135], v[164:167], off
	s_nop 1
	v_cvt_pk_bf16_f32 v164, v24, v25
	v_cvt_pk_bf16_f32 v165, v26, v27
	v_cvt_pk_bf16_f32 v166, v16, v17
	v_cvt_pk_bf16_f32 v167, v18, v19
	global_store_dwordx4 v[132:133], v[164:167], off
	v_add_co_u32_e32 v132, vcc, 0x1b000, v158
	s_nop 0
	v_cvt_pk_bf16_f32 v164, v8, v9
	v_cvt_pk_bf16_f32 v165, v10, v11
	v_cvt_pk_bf16_f32 v166, v4, v5
	v_cvt_pk_bf16_f32 v167, v6, v7
	s_nop 0
	v_addc_co_u32_e32 v133, vcc, 0, v159, vcc
	global_store_dwordx4 v[132:133], v[164:167], off
